# back-edge rotation (7.11) on the four main GEMM K-loops: counter/pointer increments and next head's scalar block moved in front of the iteration's last barrier
# baseline (speedup 1.0000x reference)
; #define PG8_STAGE(bufoff, gbase, voff) do { _Pragma("unroll") for (int _i = 0; _i < 2; ++_i) \
;         __builtin_amdgcn_global_load_lds((const unsigned*)((const char*)(gbase) + (voff)[_i]), (PG8_LAS unsigned*)(lds + (bufoff) + ldsw + _i * 8192), 16, 0, 0); } while (0)
; #define PG8_LDA(dst, b, h) do { _Pragma("unroll") for (int m = 0; m < 4; ++m) _Pragma("unroll") for (int k = 0; k < 2; ++k) dst[m][k] = *(const PG8_LAS bf16x8*)(lds + PG8_SA(b, h) + aoff + m * 2048 + k * 1024); } while (0)
; #define PG8_LDB(dst, b, h) do { _Pragma("unroll") for (int n = 0; n < 2; ++n) _Pragma("unroll") for (int k = 0; k < 2; ++k) dst[n][k] = *(const PG8_LAS bf16x8*)(lds + PG8_SB(b, h) + boff + n * 2048 + k * 1024); } while (0)
; #define PG8_MMA(ai, bj, At, Bt) do { __builtin_amdgcn_s_setprio(1); _Pragma("unroll") for (int m = 0; m < 4; ++m) _Pragma("unroll") for (int n = 0; n < 2; ++n) _Pragma("unroll") for (int k = 0; k < 2; ++k) \
;         acc[ai][bj][m][n] = __builtin_amdgcn_mfma_f32_16x16x32_bf16(Bt[n][k], At[m][k], acc[ai][bj][m][n], 0, 0, 0); __builtin_amdgcn_s_setprio(0); } while (0)
; #define PG8_WAIT_V(n) asm volatile("s_waitcnt vmcnt(" #n ")" ::: "memory")
; #define PG8_WAIT_L(n) asm volatile("s_waitcnt lgkmcnt(" #n ")" ::: "memory")
; #define PG8_BAR __builtin_amdgcn_s_barrier()
; #define PG8_SCHED __builtin_amdgcn_sched_barrier(0)
; template <class Epi, class Sched, bool ALIGN_EPI = false, bool SP2 = false>
; __device__ __forceinline__ void gemm_phase(PG8_LAS unsigned char* lds, const Gemm g, const Sched& S, const Epi& E) {
;     ...
;         for (int t = 0; t < nt; t += 2) {
;             const bool last = (t == nt - 2);
;             const char* a1 = cA + (size_t)(t + 1) * kstep;
;             const char* a2 = last ? nA : cA + (size_t)(t + 2) * kstep; const char* b2 = last ? nB : cB + (size_t)(t + 2) * kstep;
;             const char* a3 = a2 + kstep; const char* b3 = b2 + kstep;
;             if (last && has_next) S.a_ready(nxt);
;             if constexpr (SP2) {
;             PG8_LDB(B0, 0, 0); PG8_LDB(B1, 0, 1); PG8_SCHED; PG8_LDA(At, 0, 0); PG8_STAGE(PG8_SA(1, 1), a1 + hstep, voffA);
;             PG8_WAIT_V(8); PG8_WAIT_L(0); PG8_BAR; PG8_MMA(0, 0, At, B0); PG8_MMA(0, 1, At, B1); PG8_BAR; PG8_SCHED;
;             PG8_LDA(At, 0, 1); PG8_STAGE(PG8_SB(0, 0), b2, voffB); PG8_STAGE(PG8_SB(0, 1), b2 + hstep, voffB); PG8_STAGE(PG8_SA(0, 0), a2, voffA);
.Lgemm_body_1:
	ds_read_b128 v[142:145], v167
	ds_read_b128 v[168:171], v167 offset:1024
	ds_read_b128 v[172:175], v167 offset:2048
	ds_read_b128 v[176:179], v167 offset:3072
	v_add_u32_e32 v167, s62, v147
	ds_read_b128 v[180:183], v167
	ds_read_b128 v[184:187], v167 offset:1024
	ds_read_b128 v[188:191], v167 offset:2048
	ds_read_b128 v[204:207], v167 offset:3072
	v_lshl_add_u64 v[192:193], s[24:25], 0, v[138:139]
	s_add_i32 m0, s1, 0xc000
	ds_read_b128 v[216:219], v166
	ds_read_b128 v[220:223], v166 offset:1024
	ds_read_b128 v[224:227], v166 offset:2048
	ds_read_b128 v[228:231], v166 offset:3072
	ds_read_b128 v[232:235], v166 offset:4096
	ds_read_b128 v[236:239], v166 offset:5120
	ds_read_b128 v[240:243], v166 offset:6144
	ds_read_b128 v[244:247], v166 offset:7168
	global_load_lds_dwordx4 v[192:193], off
	v_lshl_add_u64 v[192:193], s[24:25], 0, v[140:141]
	s_add_i32 m0, s1, 0xe000
	s_nop 0
	global_load_lds_dwordx4 v[192:193], off
	s_waitcnt vmcnt(8)
	s_waitcnt lgkmcnt(0)
	s_barrier
	s_setprio 1
	s_waitcnt lgkmcnt(0)
	v_mfma_f32_16x16x32_bf16 v[126:129], v[142:145], v[216:219], v[126:129]
	v_mfma_f32_16x16x32_bf16 v[122:125], v[172:175], v[216:219], v[122:125]
	v_mfma_f32_16x16x32_bf16 v[114:117], v[142:145], v[224:227], v[114:117]
	v_mfma_f32_16x16x32_bf16 v[106:109], v[172:175], v[224:227], v[106:109]
	v_mfma_f32_16x16x32_bf16 v[98:101], v[142:145], v[232:235], v[98:101]
	v_mfma_f32_16x16x32_bf16 v[90:93], v[172:175], v[232:235], v[90:93]
	v_mfma_f32_16x16x32_bf16 v[82:85], v[142:145], v[240:243], v[82:85]
	v_mfma_f32_16x16x32_bf16 v[74:77], v[172:175], v[240:243], v[74:77]
	v_mfma_f32_16x16x32_bf16 v[126:129], v[168:171], v[220:223], v[126:129]
	v_mfma_f32_16x16x32_bf16 v[122:125], v[176:179], v[220:223], v[122:125]
	v_mfma_f32_16x16x32_bf16 v[114:117], v[168:171], v[228:231], v[114:117]
	v_mfma_f32_16x16x32_bf16 v[106:109], v[176:179], v[228:231], v[106:109]
	v_mfma_f32_16x16x32_bf16 v[98:101], v[168:171], v[236:239], v[98:101]
	v_mfma_f32_16x16x32_bf16 v[90:93], v[176:179], v[236:239], v[90:93]
	v_mfma_f32_16x16x32_bf16 v[82:85], v[168:171], v[244:247], v[82:85]
	v_mfma_f32_16x16x32_bf16 v[74:77], v[176:179], v[244:247], v[74:77]
	s_setprio 0
	s_setprio 1
	v_mfma_f32_16x16x32_bf16 v[118:121], v[180:183], v[216:219], v[118:121]
	v_mfma_f32_16x16x32_bf16 v[110:113], v[188:191], v[216:219], v[110:113]
	v_mfma_f32_16x16x32_bf16 v[102:105], v[180:183], v[224:227], v[102:105]
	v_mfma_f32_16x16x32_bf16 v[94:97], v[188:191], v[224:227], v[94:97]
	v_mfma_f32_16x16x32_bf16 v[86:89], v[180:183], v[232:235], v[86:89]
	v_mfma_f32_16x16x32_bf16 v[78:81], v[188:191], v[232:235], v[78:81]
	v_mfma_f32_16x16x32_bf16 v[70:73], v[180:183], v[240:243], v[70:73]
	v_mfma_f32_16x16x32_bf16 v[66:69], v[188:191], v[240:243], v[66:69]
	v_mfma_f32_16x16x32_bf16 v[118:121], v[184:187], v[220:223], v[118:121]
	v_mfma_f32_16x16x32_bf16 v[110:113], v[204:207], v[220:223], v[110:113]
	v_mfma_f32_16x16x32_bf16 v[102:105], v[184:187], v[228:231], v[102:105]
	v_mfma_f32_16x16x32_bf16 v[94:97], v[204:207], v[228:231], v[94:97]
	v_mfma_f32_16x16x32_bf16 v[86:89], v[184:187], v[236:239], v[86:89]
	v_mfma_f32_16x16x32_bf16 v[78:81], v[204:207], v[236:239], v[78:81]
	v_mfma_f32_16x16x32_bf16 v[70:73], v[184:187], v[244:247], v[70:73]
	v_mfma_f32_16x16x32_bf16 v[66:69], v[204:207], v[244:247], v[66:69]
	s_setprio 0
	s_barrier
	s_add_i32 s55, s55, s0
	v_lshl_add_u64 v[192:193], s[44:45], 0, v[0:1]
	s_mov_b32 m0, s55
	ds_read_b128 v[216:219], v166 offset:16384
	ds_read_b128 v[220:223], v166 offset:17408
	ds_read_b128 v[224:227], v166 offset:18432
	ds_read_b128 v[228:231], v166 offset:19456
	ds_read_b128 v[232:235], v166 offset:20480
	ds_read_b128 v[236:239], v166 offset:21504
	ds_read_b128 v[240:243], v166 offset:22528
	ds_read_b128 v[244:247], v166 offset:23552
	global_load_lds_dwordx4 v[192:193], off
	s_add_i32 m0, s55, 0x2000
	s_add_u32 s58, s44, 0x80000
	v_lshl_add_u64 v[248:249], s[44:45], 0, v[130:131]
	s_addc_u32 s59, s45, 0
	s_add_i32 s55, s62, s0
	global_load_lds_dwordx4 v[248:249], off
	v_lshl_add_u64 v[250:251], s[58:59], 0, v[0:1]
	s_mov_b32 m0, s55
	v_lshl_add_u64 v[200:201], s[46:47], 0, v[132:133]
	global_load_lds_dwordx4 v[250:251], off
	v_lshl_add_u64 v[250:251], s[58:59], 0, v[130:131]
	s_add_i32 m0, s55, 0x2000
	s_nop 0
	global_load_lds_dwordx4 v[250:251], off
	v_lshl_add_u64 v[250:251], s[46:47], 0, v[134:135]
	s_mov_b32 m0, s1
	s_nop 0
	global_load_lds_dwordx4 v[250:251], off
	s_mov_b32 m0, s2
	s_nop 0
	global_load_lds_dwordx4 v[200:201], off
	s_waitcnt vmcnt(8)
	s_waitcnt lgkmcnt(0)
	s_barrier
; #define PG8_STAGE(bufoff, gbase, voff) do { _Pragma("unroll") for (int _i = 0; _i < 2; ++_i) \
;         __builtin_amdgcn_global_load_lds((const unsigned*)((const char*)(gbase) + (voff)[_i]), (PG8_LAS unsigned*)(lds + (bufoff) + ldsw + _i * 8192), 16, 0, 0); } while (0)
; #define PG8_LDA(dst, b, h) do { _Pragma("unroll") for (int m = 0; m < 4; ++m) _Pragma("unroll") for (int k = 0; k < 2; ++k) dst[m][k] = *(const PG8_LAS bf16x8*)(lds + PG8_SA(b, h) + aoff + m * 2048 + k * 1024); } while (0)
; #define PG8_LDB(dst, b, h) do { _Pragma("unroll") for (int n = 0; n < 2; ++n) _Pragma("unroll") for (int k = 0; k < 2; ++k) dst[n][k] = *(const PG8_LAS bf16x8*)(lds + PG8_SB(b, h) + boff + n * 2048 + k * 1024); } while (0)
; #define PG8_MMA(ai, bj, At, Bt) do { __builtin_amdgcn_s_setprio(1); _Pragma("unroll") for (int m = 0; m < 4; ++m) _Pragma("unroll") for (int n = 0; n < 2; ++n) _Pragma("unroll") for (int k = 0; k < 2; ++k) \
;         acc[ai][bj][m][n] = __builtin_amdgcn_mfma_f32_16x16x32_bf16(Bt[n][k], At[m][k], acc[ai][bj][m][n], 0, 0, 0); __builtin_amdgcn_s_setprio(0); } while (0)
; #define PG8_WAIT_V(n) asm volatile("s_waitcnt vmcnt(" #n ")" ::: "memory")
; #define PG8_WAIT_L(n) asm volatile("s_waitcnt lgkmcnt(" #n ")" ::: "memory")
; #define PG8_BAR __builtin_amdgcn_s_barrier()
; #define PG8_SCHED __builtin_amdgcn_sched_barrier(0)
; template <class Epi, class Sched, bool ALIGN_EPI = false, bool SP2 = false>
; __device__ __forceinline__ void gemm_phase(PG8_LAS unsigned char* lds, const Gemm g, const Sched& S, const Epi& E) {
;     ...
;             PG8_WAIT_V(8); PG8_WAIT_L(0); PG8_BAR; PG8_MMA(1, 0, At, B0); PG8_MMA(1, 1, At, B1); PG8_BAR; PG8_SCHED;
;             PG8_LDB(B0, 1, 0); PG8_LDB(B1, 1, 1); PG8_SCHED; PG8_LDA(At, 1, 0); PG8_STAGE(PG8_SA(0, 1), a2 + hstep, voffA);
;             PG8_WAIT_V(8); PG8_WAIT_L(0); PG8_BAR; PG8_MMA(0, 0, At, B0); PG8_MMA(0, 1, At, B1); PG8_BAR; PG8_SCHED;
	s_setprio 1
	s_waitcnt lgkmcnt(0)
	v_mfma_f32_16x16x32_bf16 v[62:65], v[142:145], v[216:219], v[62:65]
	v_mfma_f32_16x16x32_bf16 v[58:61], v[172:175], v[216:219], v[58:61]
	v_mfma_f32_16x16x32_bf16 v[50:53], v[142:145], v[224:227], v[50:53]
	v_mfma_f32_16x16x32_bf16 v[42:45], v[172:175], v[224:227], v[42:45]
	v_mfma_f32_16x16x32_bf16 v[34:37], v[142:145], v[232:235], v[34:37]
	v_mfma_f32_16x16x32_bf16 v[26:29], v[172:175], v[232:235], v[26:29]
	v_mfma_f32_16x16x32_bf16 v[18:21], v[142:145], v[240:243], v[18:21]
	v_mfma_f32_16x16x32_bf16 v[10:13], v[172:175], v[240:243], v[10:13]
	v_mfma_f32_16x16x32_bf16 v[62:65], v[168:171], v[220:223], v[62:65]
	v_mfma_f32_16x16x32_bf16 v[58:61], v[176:179], v[220:223], v[58:61]
	v_mfma_f32_16x16x32_bf16 v[50:53], v[168:171], v[228:231], v[50:53]
	v_mfma_f32_16x16x32_bf16 v[42:45], v[176:179], v[228:231], v[42:45]
	v_mfma_f32_16x16x32_bf16 v[34:37], v[168:171], v[236:239], v[34:37]
	v_mfma_f32_16x16x32_bf16 v[26:29], v[176:179], v[236:239], v[26:29]
	v_mfma_f32_16x16x32_bf16 v[18:21], v[168:171], v[244:247], v[18:21]
	v_mfma_f32_16x16x32_bf16 v[10:13], v[176:179], v[244:247], v[10:13]
	s_setprio 0
	s_setprio 1
	v_mfma_f32_16x16x32_bf16 v[54:57], v[180:183], v[216:219], v[54:57]
	v_mfma_f32_16x16x32_bf16 v[46:49], v[188:191], v[216:219], v[46:49]
	v_mfma_f32_16x16x32_bf16 v[38:41], v[180:183], v[224:227], v[38:41]
	v_mfma_f32_16x16x32_bf16 v[30:33], v[188:191], v[224:227], v[30:33]
	v_mfma_f32_16x16x32_bf16 v[22:25], v[180:183], v[232:235], v[22:25]
	v_mfma_f32_16x16x32_bf16 v[14:17], v[188:191], v[232:235], v[14:17]
	v_mfma_f32_16x16x32_bf16 v[6:9], v[180:183], v[240:243], v[6:9]
	v_mfma_f32_16x16x32_bf16 v[2:5], v[188:191], v[240:243], v[2:5]
	v_mfma_f32_16x16x32_bf16 v[54:57], v[184:187], v[220:223], v[54:57]
	v_mfma_f32_16x16x32_bf16 v[46:49], v[204:207], v[220:223], v[46:49]
	v_mfma_f32_16x16x32_bf16 v[38:41], v[184:187], v[228:231], v[38:41]
	v_mfma_f32_16x16x32_bf16 v[30:33], v[204:207], v[228:231], v[30:33]
	v_mfma_f32_16x16x32_bf16 v[22:25], v[184:187], v[236:239], v[22:25]
	v_mfma_f32_16x16x32_bf16 v[14:17], v[204:207], v[236:239], v[14:17]
	v_mfma_f32_16x16x32_bf16 v[6:9], v[184:187], v[244:247], v[6:9]
	v_mfma_f32_16x16x32_bf16 v[2:5], v[204:207], v[244:247], v[2:5]
	s_setprio 0
	s_barrier
	s_add_i32 s55, 0, 0x18000
	v_add_u32_e32 v167, s55, v147
	s_add_i32 s58, 0, 0x1c000
	ds_read_b128 v[142:145], v167
	ds_read_b128 v[168:171], v167 offset:1024
	ds_read_b128 v[172:175], v167 offset:2048
	ds_read_b128 v[176:179], v167 offset:3072
	v_add_u32_e32 v167, s58, v147
	ds_read_b128 v[180:183], v167
	ds_read_b128 v[184:187], v167 offset:1024
	ds_read_b128 v[188:191], v167 offset:2048
	ds_read_b128 v[204:207], v167 offset:3072
	s_add_u32 s46, s46, 0x80000
	s_addc_u32 s47, s47, 0
	s_mov_b32 m0, s3
	v_lshl_add_u64 v[202:203], s[46:47], 0, v[134:135]
	ds_read_b128 v[216:219], v166 offset:32768
	ds_read_b128 v[220:223], v166 offset:33792
	ds_read_b128 v[224:227], v166 offset:34816
	ds_read_b128 v[228:231], v166 offset:35840
	ds_read_b128 v[232:235], v166 offset:36864
	ds_read_b128 v[236:239], v166 offset:37888
	ds_read_b128 v[240:243], v166 offset:38912
	ds_read_b128 v[244:247], v166 offset:39936
	global_load_lds_dwordx4 v[202:203], off
	v_lshl_add_u64 v[202:203], s[46:47], 0, v[132:133]
	s_mov_b32 m0, s10
	s_nop 0
	global_load_lds_dwordx4 v[202:203], off
	s_waitcnt vmcnt(8)
	s_waitcnt lgkmcnt(0)
	s_barrier
	s_setprio 1
	s_waitcnt lgkmcnt(0)
	v_mfma_f32_16x16x32_bf16 v[126:129], v[142:145], v[216:219], v[126:129]
	v_mfma_f32_16x16x32_bf16 v[122:125], v[172:175], v[216:219], v[122:125]
	v_mfma_f32_16x16x32_bf16 v[114:117], v[142:145], v[224:227], v[114:117]
	v_mfma_f32_16x16x32_bf16 v[106:109], v[172:175], v[224:227], v[106:109]
	v_mfma_f32_16x16x32_bf16 v[98:101], v[142:145], v[232:235], v[98:101]
	v_mfma_f32_16x16x32_bf16 v[90:93], v[172:175], v[232:235], v[90:93]
	v_mfma_f32_16x16x32_bf16 v[82:85], v[142:145], v[240:243], v[82:85]
	v_mfma_f32_16x16x32_bf16 v[74:77], v[172:175], v[240:243], v[74:77]
	v_mfma_f32_16x16x32_bf16 v[126:129], v[168:171], v[220:223], v[126:129]
	v_mfma_f32_16x16x32_bf16 v[122:125], v[176:179], v[220:223], v[122:125]
	v_mfma_f32_16x16x32_bf16 v[114:117], v[168:171], v[228:231], v[114:117]
	v_mfma_f32_16x16x32_bf16 v[106:109], v[176:179], v[228:231], v[106:109]
	v_mfma_f32_16x16x32_bf16 v[98:101], v[168:171], v[236:239], v[98:101]
	v_mfma_f32_16x16x32_bf16 v[90:93], v[176:179], v[236:239], v[90:93]
	v_mfma_f32_16x16x32_bf16 v[82:85], v[168:171], v[244:247], v[82:85]
	v_mfma_f32_16x16x32_bf16 v[74:77], v[176:179], v[244:247], v[74:77]
	s_setprio 0
	s_setprio 1
	v_mfma_f32_16x16x32_bf16 v[118:121], v[180:183], v[216:219], v[118:121]
	v_mfma_f32_16x16x32_bf16 v[110:113], v[188:191], v[216:219], v[110:113]
	v_mfma_f32_16x16x32_bf16 v[102:105], v[180:183], v[224:227], v[102:105]
	v_mfma_f32_16x16x32_bf16 v[94:97], v[188:191], v[224:227], v[94:97]
	v_mfma_f32_16x16x32_bf16 v[86:89], v[180:183], v[232:235], v[86:89]
	v_mfma_f32_16x16x32_bf16 v[78:81], v[188:191], v[232:235], v[78:81]
	v_mfma_f32_16x16x32_bf16 v[70:73], v[180:183], v[240:243], v[70:73]
	v_mfma_f32_16x16x32_bf16 v[66:69], v[188:191], v[240:243], v[66:69]
	v_mfma_f32_16x16x32_bf16 v[118:121], v[184:187], v[220:223], v[118:121]
	v_mfma_f32_16x16x32_bf16 v[110:113], v[204:207], v[220:223], v[110:113]
	v_mfma_f32_16x16x32_bf16 v[102:105], v[184:187], v[228:231], v[102:105]
	v_mfma_f32_16x16x32_bf16 v[94:97], v[204:207], v[228:231], v[94:97]
	v_mfma_f32_16x16x32_bf16 v[86:89], v[184:187], v[236:239], v[86:89]
	v_mfma_f32_16x16x32_bf16 v[78:81], v[204:207], v[236:239], v[78:81]
	v_mfma_f32_16x16x32_bf16 v[70:73], v[184:187], v[244:247], v[70:73]
	v_mfma_f32_16x16x32_bf16 v[66:69], v[204:207], v[244:247], v[66:69]
	s_setprio 0
	s_barrier
; #define PG8_STAGE(bufoff, gbase, voff) do { _Pragma("unroll") for (int _i = 0; _i < 2; ++_i) \
;         __builtin_amdgcn_global_load_lds((const unsigned*)((const char*)(gbase) + (voff)[_i]), (PG8_LAS unsigned*)(lds + (bufoff) + ldsw + _i * 8192), 16, 0, 0); } while (0)
; #define PG8_LDA(dst, b, h) do { _Pragma("unroll") for (int m = 0; m < 4; ++m) _Pragma("unroll") for (int k = 0; k < 2; ++k) dst[m][k] = *(const PG8_LAS bf16x8*)(lds + PG8_SA(b, h) + aoff + m * 2048 + k * 1024); } while (0)
; #define PG8_MMA(ai, bj, At, Bt) do { __builtin_amdgcn_s_setprio(1); _Pragma("unroll") for (int m = 0; m < 4; ++m) _Pragma("unroll") for (int n = 0; n < 2; ++n) _Pragma("unroll") for (int k = 0; k < 2; ++k) \
;         acc[ai][bj][m][n] = __builtin_amdgcn_mfma_f32_16x16x32_bf16(Bt[n][k], At[m][k], acc[ai][bj][m][n], 0, 0, 0); __builtin_amdgcn_s_setprio(0); } while (0)
; #define PG8_WAIT_V(n) asm volatile("s_waitcnt vmcnt(" #n ")" ::: "memory")
; #define PG8_WAIT_L(n) asm volatile("s_waitcnt lgkmcnt(" #n ")" ::: "memory")
; #define PG8_BAR __builtin_amdgcn_s_barrier()
; #define PG8_SCHED __builtin_amdgcn_sched_barrier(0)
; template <class Epi, class Sched, bool ALIGN_EPI = false, bool SP2 = false>
; __device__ __forceinline__ void gemm_phase(PG8_LAS unsigned char* lds, const Gemm g, const Sched& S, const Epi& E) {
;     ...
;         for (int t = 0; t < nt; t += 2) {
;             const bool last = (t == nt - 2);
;             const char* a1 = cA + (size_t)(t + 1) * kstep;
;             const char* a2 = last ? nA : cA + (size_t)(t + 2) * kstep; const char* b2 = last ? nB : cB + (size_t)(t + 2) * kstep;
;             const char* a3 = a2 + kstep; const char* b3 = b2 + kstep;
;             if (last && has_next) S.a_ready(nxt);
;     ...
;             PG8_LDA(At, 1, 1); PG8_STAGE(PG8_SB(1, 0), b3, voffB); PG8_STAGE(PG8_SB(1, 1), b3 + hstep, voffB); PG8_STAGE(PG8_SA(1, 0), a3, voffA);
;             PG8_WAIT_V(8); PG8_WAIT_L(0); PG8_BAR; PG8_MMA(1, 0, At, B0); PG8_MMA(1, 1, At, B1); PG8_BAR; PG8_SCHED;
	s_add_i32 s46, s55, s0
	v_lshl_add_u64 v[192:193], v[192:193], 0, s[56:57]
	s_mov_b32 m0, s46
	ds_read_b128 v[216:219], v166 offset:49152
	ds_read_b128 v[220:223], v166 offset:50176
	ds_read_b128 v[224:227], v166 offset:51200
	ds_read_b128 v[228:231], v166 offset:52224
	ds_read_b128 v[232:235], v166 offset:53248
	ds_read_b128 v[236:239], v166 offset:54272
	ds_read_b128 v[240:243], v166 offset:55296
	ds_read_b128 v[244:247], v166 offset:56320
	global_load_lds_dwordx4 v[192:193], off
	s_add_i32 m0, s46, 0x2000
	s_add_u32 s44, s44, 0x80080
	v_lshl_add_u64 v[192:193], v[248:249], 0, s[56:57]
	s_addc_u32 s45, s45, 0
	s_add_i32 s46, s58, s0
	global_load_lds_dwordx4 v[192:193], off
	v_lshl_add_u64 v[192:193], s[44:45], 0, v[0:1]
	s_mov_b32 m0, s46
	s_nop 0
	global_load_lds_dwordx4 v[192:193], off
	v_lshl_add_u64 v[192:193], s[44:45], 0, v[130:131]
	s_add_i32 m0, s46, 0x2000
	s_nop 0
	global_load_lds_dwordx4 v[192:193], off
	v_lshl_add_u64 v[192:193], v[250:251], 0, s[56:57]
	s_mov_b32 m0, s11
	s_nop 0
	global_load_lds_dwordx4 v[192:193], off
	v_lshl_add_u64 v[192:193], v[200:201], 0, s[56:57]
	s_mov_b32 m0, s26
	s_nop 0
	global_load_lds_dwordx4 v[192:193], off
	s_waitcnt vmcnt(8)
	s_waitcnt lgkmcnt(0)
	s_barrier
	s_setprio 1
	s_waitcnt lgkmcnt(0)
	v_mfma_f32_16x16x32_bf16 v[62:65], v[142:145], v[216:219], v[62:65]
	v_mfma_f32_16x16x32_bf16 v[58:61], v[172:175], v[216:219], v[58:61]
	v_mfma_f32_16x16x32_bf16 v[50:53], v[142:145], v[224:227], v[50:53]
	v_mfma_f32_16x16x32_bf16 v[42:45], v[172:175], v[224:227], v[42:45]
	v_mfma_f32_16x16x32_bf16 v[34:37], v[142:145], v[232:235], v[34:37]
	v_mfma_f32_16x16x32_bf16 v[26:29], v[172:175], v[232:235], v[26:29]
	v_mfma_f32_16x16x32_bf16 v[18:21], v[142:145], v[240:243], v[18:21]
	v_mfma_f32_16x16x32_bf16 v[10:13], v[172:175], v[240:243], v[10:13]
	v_mfma_f32_16x16x32_bf16 v[62:65], v[168:171], v[220:223], v[62:65]
	v_mfma_f32_16x16x32_bf16 v[58:61], v[176:179], v[220:223], v[58:61]
	v_mfma_f32_16x16x32_bf16 v[50:53], v[168:171], v[228:231], v[50:53]
	v_mfma_f32_16x16x32_bf16 v[42:45], v[176:179], v[228:231], v[42:45]
	v_mfma_f32_16x16x32_bf16 v[34:37], v[168:171], v[236:239], v[34:37]
	v_mfma_f32_16x16x32_bf16 v[26:29], v[176:179], v[236:239], v[26:29]
	v_mfma_f32_16x16x32_bf16 v[18:21], v[168:171], v[244:247], v[18:21]
	v_mfma_f32_16x16x32_bf16 v[10:13], v[176:179], v[244:247], v[10:13]
	s_setprio 0
	s_setprio 1
	v_mfma_f32_16x16x32_bf16 v[54:57], v[180:183], v[216:219], v[54:57]
	v_mfma_f32_16x16x32_bf16 v[46:49], v[188:191], v[216:219], v[46:49]
	v_mfma_f32_16x16x32_bf16 v[38:41], v[180:183], v[224:227], v[38:41]
	v_mfma_f32_16x16x32_bf16 v[30:33], v[188:191], v[224:227], v[30:33]
	v_mfma_f32_16x16x32_bf16 v[22:25], v[180:183], v[232:235], v[22:25]
	v_mfma_f32_16x16x32_bf16 v[14:17], v[188:191], v[232:235], v[14:17]
	v_mfma_f32_16x16x32_bf16 v[6:9], v[180:183], v[240:243], v[6:9]
	v_mfma_f32_16x16x32_bf16 v[2:5], v[188:191], v[240:243], v[2:5]
	v_mfma_f32_16x16x32_bf16 v[54:57], v[184:187], v[220:223], v[54:57]
	v_mfma_f32_16x16x32_bf16 v[46:49], v[204:207], v[220:223], v[46:49]
	v_mfma_f32_16x16x32_bf16 v[38:41], v[184:187], v[228:231], v[38:41]
	v_mfma_f32_16x16x32_bf16 v[30:33], v[204:207], v[228:231], v[30:33]
	v_mfma_f32_16x16x32_bf16 v[22:25], v[184:187], v[236:239], v[22:25]
	v_mfma_f32_16x16x32_bf16 v[14:17], v[204:207], v[236:239], v[14:17]
	v_mfma_f32_16x16x32_bf16 v[6:9], v[184:187], v[244:247], v[6:9]
	v_mfma_f32_16x16x32_bf16 v[2:5], v[204:207], v[244:247], v[2:5]
	s_setprio 0
	s_add_i32 s54, s54, 2
	s_add_u32 s24, s24, 0x100
	s_addc_u32 s25, s25, 0
	s_add_u32 s50, s50, 0x100
	s_addc_u32 s51, s51, 0
	s_cmp_gt_u32 s54, 29
	s_cbranch_scc1 .Lgemm_exit_1
	s_add_u32 s44, s24, 0xfff80080
	s_addc_u32 s45, s25, -1
	s_add_i32 s55, 0, 0x10000
	s_cmp_eq_u32 s54, 28
	s_cselect_b32 s47, s21, s45
	s_cselect_b32 s46, s48, s44
	v_add_u32_e32 v167, s55, v147
	s_cselect_b32 s45, s19, s51
	s_cselect_b32 s44, s49, s50
	s_add_i32 s62, 0, 0x14000
	s_barrier
	s_branch .Lgemm_body_1
.Lgemm_exit_1:
	s_barrier
	s_and_b64 vcc, exec, s[16:17]
	s_cbranch_vccz .LBB0_149
	s_barrier

; #define PG8_STAGE(bufoff, gbase, voff) do { _Pragma("unroll") for (int _i = 0; _i < 2; ++_i) \
;         __builtin_amdgcn_global_load_lds((const unsigned*)((const char*)(gbase) + (voff)[_i]), (PG8_LAS unsigned*)(lds + (bufoff) + ldsw + _i * 8192), 16, 0, 0); } while (0)
; #define PG8_LDA(dst, b, h) do { _Pragma("unroll") for (int m = 0; m < 4; ++m) _Pragma("unroll") for (int k = 0; k < 2; ++k) dst[m][k] = *(const PG8_LAS bf16x8*)(lds + PG8_SA(b, h) + aoff + m * 2048 + k * 1024); } while (0)
; #define PG8_LDB(dst, b, h) do { _Pragma("unroll") for (int n = 0; n < 2; ++n) _Pragma("unroll") for (int k = 0; k < 2; ++k) dst[n][k] = *(const PG8_LAS bf16x8*)(lds + PG8_SB(b, h) + boff + n * 2048 + k * 1024); } while (0)
; #define PG8_MMA(ai, bj, At, Bt) do { __builtin_amdgcn_s_setprio(1); _Pragma("unroll") for (int m = 0; m < 4; ++m) _Pragma("unroll") for (int n = 0; n < 2; ++n) _Pragma("unroll") for (int k = 0; k < 2; ++k) \
;         acc[ai][bj][m][n] = __builtin_amdgcn_mfma_f32_16x16x32_bf16(Bt[n][k], At[m][k], acc[ai][bj][m][n], 0, 0, 0); __builtin_amdgcn_s_setprio(0); } while (0)
; #define PG8_WAIT_V(n) asm volatile("s_waitcnt vmcnt(" #n ")" ::: "memory")
; #define PG8_WAIT_L(n) asm volatile("s_waitcnt lgkmcnt(" #n ")" ::: "memory")
; #define PG8_BAR __builtin_amdgcn_s_barrier()
; #define PG8_SCHED __builtin_amdgcn_sched_barrier(0)
; template <class Epi, class Sched, bool ALIGN_EPI = false, bool SP2 = false>
; __device__ __forceinline__ void gemm_phase(PG8_LAS unsigned char* lds, const Gemm g, const Sched& S, const Epi& E) {
;     ...
;         for (int t = 0; t < nt; t += 2) {
;             const bool last = (t == nt - 2);
;             const char* a1 = cA + (size_t)(t + 1) * kstep;
;             const char* a2 = last ? nA : cA + (size_t)(t + 2) * kstep; const char* b2 = last ? nB : cB + (size_t)(t + 2) * kstep;
;             const char* a3 = a2 + kstep; const char* b3 = b2 + kstep;
;             if (last && has_next) S.a_ready(nxt);
;             if constexpr (SP2) {
;             PG8_LDB(B0, 0, 0); PG8_LDB(B1, 0, 1); PG8_SCHED; PG8_LDA(At, 0, 0); PG8_STAGE(PG8_SA(1, 1), a1 + hstep, voffA);
;             PG8_WAIT_V(8); PG8_WAIT_L(0); PG8_BAR; PG8_MMA(0, 0, At, B0); PG8_MMA(0, 1, At, B1); PG8_BAR; PG8_SCHED;
;             PG8_LDA(At, 0, 1); PG8_STAGE(PG8_SB(0, 0), b2, voffB); PG8_STAGE(PG8_SB(0, 1), b2 + hstep, voffB); PG8_STAGE(PG8_SA(0, 0), a2, voffA);
.Lgemm_body_2:
	ds_read_b128 v[130:133], v152
	ds_read_b128 v[134:137], v152 offset:1024
	ds_read_b128 v[138:141], v152 offset:2048
	ds_read_b128 v[152:155], v152 offset:3072
	ds_read_b128 v[156:159], v160
	ds_read_b128 v[166:169], v160 offset:1024
	ds_read_b128 v[170:173], v160 offset:2048
	ds_read_b128 v[174:177], v160 offset:3072
	v_lshl_add_u64 v[160:161], s[24:25], 0, v[148:149]
	s_add_i32 m0, s3, 0xc000
	ds_read_b128 v[178:181], v165
	ds_read_b128 v[182:185], v165 offset:1024
	ds_read_b128 v[186:189], v165 offset:2048
	ds_read_b128 v[190:193], v165 offset:3072
	ds_read_b128 v[204:207], v165 offset:4096
	ds_read_b128 v[218:221], v165 offset:5120
	ds_read_b128 v[222:225], v165 offset:6144
	ds_read_b128 v[226:229], v165 offset:7168
	global_load_lds_dwordx4 v[160:161], off
	v_lshl_add_u64 v[160:161], s[24:25], 0, v[150:151]
	s_add_i32 m0, s3, 0xe000
	s_nop 0
	global_load_lds_dwordx4 v[160:161], off
	s_waitcnt vmcnt(8)
	s_waitcnt lgkmcnt(0)
	s_barrier
	s_setprio 1
	s_waitcnt lgkmcnt(0)
	v_mfma_f32_16x16x32_bf16 v[126:129], v[130:133], v[178:181], v[126:129]
	v_mfma_f32_16x16x32_bf16 v[122:125], v[138:141], v[178:181], v[122:125]
	v_mfma_f32_16x16x32_bf16 v[110:113], v[130:133], v[186:189], v[110:113]
	v_mfma_f32_16x16x32_bf16 v[106:109], v[138:141], v[186:189], v[106:109]
	v_mfma_f32_16x16x32_bf16 v[94:97], v[130:133], v[204:207], v[94:97]
	v_mfma_f32_16x16x32_bf16 v[90:93], v[138:141], v[204:207], v[90:93]
	v_mfma_f32_16x16x32_bf16 v[78:81], v[130:133], v[222:225], v[78:81]
	v_mfma_f32_16x16x32_bf16 v[74:77], v[138:141], v[222:225], v[74:77]
	v_mfma_f32_16x16x32_bf16 v[126:129], v[134:137], v[182:185], v[126:129]
	v_mfma_f32_16x16x32_bf16 v[122:125], v[152:155], v[182:185], v[122:125]
	v_mfma_f32_16x16x32_bf16 v[110:113], v[134:137], v[190:193], v[110:113]
	v_mfma_f32_16x16x32_bf16 v[106:109], v[152:155], v[190:193], v[106:109]
	v_mfma_f32_16x16x32_bf16 v[94:97], v[134:137], v[218:221], v[94:97]
	v_mfma_f32_16x16x32_bf16 v[90:93], v[152:155], v[218:221], v[90:93]
	v_mfma_f32_16x16x32_bf16 v[78:81], v[134:137], v[226:229], v[78:81]
	v_mfma_f32_16x16x32_bf16 v[74:77], v[152:155], v[226:229], v[74:77]
	s_setprio 0
	s_setprio 1
	v_mfma_f32_16x16x32_bf16 v[118:121], v[156:159], v[178:181], v[118:121]
	v_mfma_f32_16x16x32_bf16 v[114:117], v[170:173], v[178:181], v[114:117]
	v_mfma_f32_16x16x32_bf16 v[102:105], v[156:159], v[186:189], v[102:105]
	v_mfma_f32_16x16x32_bf16 v[98:101], v[170:173], v[186:189], v[98:101]
	v_mfma_f32_16x16x32_bf16 v[86:89], v[156:159], v[204:207], v[86:89]
	v_mfma_f32_16x16x32_bf16 v[82:85], v[170:173], v[204:207], v[82:85]
	v_mfma_f32_16x16x32_bf16 v[70:73], v[156:159], v[222:225], v[70:73]
	v_mfma_f32_16x16x32_bf16 v[66:69], v[170:173], v[222:225], v[66:69]
	v_mfma_f32_16x16x32_bf16 v[118:121], v[166:169], v[182:185], v[118:121]
	v_mfma_f32_16x16x32_bf16 v[114:117], v[174:177], v[182:185], v[114:117]
	v_mfma_f32_16x16x32_bf16 v[102:105], v[166:169], v[190:193], v[102:105]
	v_mfma_f32_16x16x32_bf16 v[98:101], v[174:177], v[190:193], v[98:101]
	v_mfma_f32_16x16x32_bf16 v[86:89], v[166:169], v[218:221], v[86:89]
	v_mfma_f32_16x16x32_bf16 v[82:85], v[174:177], v[218:221], v[82:85]
	v_mfma_f32_16x16x32_bf16 v[70:73], v[166:169], v[226:229], v[70:73]
	v_mfma_f32_16x16x32_bf16 v[66:69], v[174:177], v[226:229], v[66:69]
	s_setprio 0
	s_barrier
	s_add_i32 s66, s66, s2
	v_lshl_add_u64 v[160:161], s[50:51], 0, v[0:1]
	s_mov_b32 m0, s66
	ds_read_b128 v[178:181], v165 offset:16384
	ds_read_b128 v[182:185], v165 offset:17408
	ds_read_b128 v[186:189], v165 offset:18432
	ds_read_b128 v[190:193], v165 offset:19456
	ds_read_b128 v[204:207], v165 offset:20480
	ds_read_b128 v[218:221], v165 offset:21504
	ds_read_b128 v[222:225], v165 offset:22528
	ds_read_b128 v[226:229], v165 offset:23552
	global_load_lds_dwordx4 v[160:161], off
	s_add_i32 m0, s66, 0x2000
	s_add_u32 s66, s50, 0x80000
	v_lshl_add_u64 v[200:201], s[50:51], 0, v[146:147]
	s_addc_u32 s67, s51, 0
	s_add_i32 s68, s68, s2
	global_load_lds_dwordx4 v[200:201], off
	v_lshl_add_u64 v[202:203], s[66:67], 0, v[0:1]
	s_mov_b32 m0, s68
	v_lshl_add_u64 v[230:231], s[58:59], 0, v[144:145]
	global_load_lds_dwordx4 v[202:203], off
	v_lshl_add_u64 v[202:203], s[66:67], 0, v[146:147]
	s_add_i32 m0, s68, 0x2000
	s_nop 0
	global_load_lds_dwordx4 v[202:203], off
	v_lshl_add_u64 v[202:203], s[58:59], 0, v[142:143]
	s_mov_b32 m0, s3
	s_nop 0
	global_load_lds_dwordx4 v[202:203], off
	s_mov_b32 m0, s10
	s_nop 0
	global_load_lds_dwordx4 v[230:231], off
	s_waitcnt vmcnt(8)
	s_waitcnt lgkmcnt(0)
	s_barrier
; #define PG8_STAGE(bufoff, gbase, voff) do { _Pragma("unroll") for (int _i = 0; _i < 2; ++_i) \
;         __builtin_amdgcn_global_load_lds((const unsigned*)((const char*)(gbase) + (voff)[_i]), (PG8_LAS unsigned*)(lds + (bufoff) + ldsw + _i * 8192), 16, 0, 0); } while (0)
; #define PG8_LDA(dst, b, h) do { _Pragma("unroll") for (int m = 0; m < 4; ++m) _Pragma("unroll") for (int k = 0; k < 2; ++k) dst[m][k] = *(const PG8_LAS bf16x8*)(lds + PG8_SA(b, h) + aoff + m * 2048 + k * 1024); } while (0)
; #define PG8_LDB(dst, b, h) do { _Pragma("unroll") for (int n = 0; n < 2; ++n) _Pragma("unroll") for (int k = 0; k < 2; ++k) dst[n][k] = *(const PG8_LAS bf16x8*)(lds + PG8_SB(b, h) + boff + n * 2048 + k * 1024); } while (0)
; #define PG8_MMA(ai, bj, At, Bt) do { __builtin_amdgcn_s_setprio(1); _Pragma("unroll") for (int m = 0; m < 4; ++m) _Pragma("unroll") for (int n = 0; n < 2; ++n) _Pragma("unroll") for (int k = 0; k < 2; ++k) \
;         acc[ai][bj][m][n] = __builtin_amdgcn_mfma_f32_16x16x32_bf16(Bt[n][k], At[m][k], acc[ai][bj][m][n], 0, 0, 0); __builtin_amdgcn_s_setprio(0); } while (0)
; #define PG8_WAIT_V(n) asm volatile("s_waitcnt vmcnt(" #n ")" ::: "memory")
; #define PG8_WAIT_L(n) asm volatile("s_waitcnt lgkmcnt(" #n ")" ::: "memory")
; #define PG8_BAR __builtin_amdgcn_s_barrier()
; #define PG8_SCHED __builtin_amdgcn_sched_barrier(0)
; template <class Epi, class Sched, bool ALIGN_EPI = false, bool SP2 = false>
; __device__ __forceinline__ void gemm_phase(PG8_LAS unsigned char* lds, const Gemm g, const Sched& S, const Epi& E) {
;     ...
;             PG8_WAIT_V(8); PG8_WAIT_L(0); PG8_BAR; PG8_MMA(1, 0, At, B0); PG8_MMA(1, 1, At, B1); PG8_BAR; PG8_SCHED;
;             PG8_LDB(B0, 1, 0); PG8_LDB(B1, 1, 1); PG8_SCHED; PG8_LDA(At, 1, 0); PG8_STAGE(PG8_SA(0, 1), a2 + hstep, voffA);
;             PG8_WAIT_V(8); PG8_WAIT_L(0); PG8_BAR; PG8_MMA(0, 0, At, B0); PG8_MMA(0, 1, At, B1); PG8_BAR; PG8_SCHED;
	s_setprio 1
	s_waitcnt lgkmcnt(0)
	v_mfma_f32_16x16x32_bf16 v[62:65], v[130:133], v[178:181], v[62:65]
	v_mfma_f32_16x16x32_bf16 v[58:61], v[138:141], v[178:181], v[58:61]
	v_mfma_f32_16x16x32_bf16 v[46:49], v[130:133], v[186:189], v[46:49]
	v_mfma_f32_16x16x32_bf16 v[42:45], v[138:141], v[186:189], v[42:45]
	v_mfma_f32_16x16x32_bf16 v[30:33], v[130:133], v[204:207], v[30:33]
	v_mfma_f32_16x16x32_bf16 v[26:29], v[138:141], v[204:207], v[26:29]
	v_mfma_f32_16x16x32_bf16 v[14:17], v[130:133], v[222:225], v[14:17]
	v_mfma_f32_16x16x32_bf16 v[10:13], v[138:141], v[222:225], v[10:13]
	v_mfma_f32_16x16x32_bf16 v[62:65], v[134:137], v[182:185], v[62:65]
	v_mfma_f32_16x16x32_bf16 v[58:61], v[152:155], v[182:185], v[58:61]
	v_mfma_f32_16x16x32_bf16 v[46:49], v[134:137], v[190:193], v[46:49]
	v_mfma_f32_16x16x32_bf16 v[42:45], v[152:155], v[190:193], v[42:45]
	v_mfma_f32_16x16x32_bf16 v[30:33], v[134:137], v[218:221], v[30:33]
	v_mfma_f32_16x16x32_bf16 v[26:29], v[152:155], v[218:221], v[26:29]
	v_mfma_f32_16x16x32_bf16 v[14:17], v[134:137], v[226:229], v[14:17]
	v_mfma_f32_16x16x32_bf16 v[10:13], v[152:155], v[226:229], v[10:13]
	s_setprio 0
	s_setprio 1
	v_mfma_f32_16x16x32_bf16 v[54:57], v[156:159], v[178:181], v[54:57]
	v_mfma_f32_16x16x32_bf16 v[50:53], v[170:173], v[178:181], v[50:53]
	v_mfma_f32_16x16x32_bf16 v[38:41], v[156:159], v[186:189], v[38:41]
	v_mfma_f32_16x16x32_bf16 v[34:37], v[170:173], v[186:189], v[34:37]
	v_mfma_f32_16x16x32_bf16 v[22:25], v[156:159], v[204:207], v[22:25]
	v_mfma_f32_16x16x32_bf16 v[18:21], v[170:173], v[204:207], v[18:21]
	v_mfma_f32_16x16x32_bf16 v[6:9], v[156:159], v[222:225], v[6:9]
	v_mfma_f32_16x16x32_bf16 v[2:5], v[170:173], v[222:225], v[2:5]
	v_mfma_f32_16x16x32_bf16 v[54:57], v[166:169], v[182:185], v[54:57]
	v_mfma_f32_16x16x32_bf16 v[50:53], v[174:177], v[182:185], v[50:53]
	v_mfma_f32_16x16x32_bf16 v[38:41], v[166:169], v[190:193], v[38:41]
	v_mfma_f32_16x16x32_bf16 v[34:37], v[174:177], v[190:193], v[34:37]
	v_mfma_f32_16x16x32_bf16 v[22:25], v[166:169], v[218:221], v[22:25]
	v_mfma_f32_16x16x32_bf16 v[18:21], v[174:177], v[218:221], v[18:21]
	v_mfma_f32_16x16x32_bf16 v[6:9], v[166:169], v[226:229], v[6:9]
	v_mfma_f32_16x16x32_bf16 v[2:5], v[174:177], v[226:229], v[2:5]
	s_setprio 0
	s_barrier
	s_add_i32 s66, 0, 0x18000
	s_add_i32 s67, 0, 0x1c000
	v_add_u32_e32 v152, s66, v163
	v_add_u32_e32 v174, s67, v163
	ds_read_b128 v[130:133], v152
	ds_read_b128 v[134:137], v152 offset:1024
	ds_read_b128 v[138:141], v152 offset:2048
	ds_read_b128 v[152:155], v152 offset:3072
	ds_read_b128 v[156:159], v174
	ds_read_b128 v[166:169], v174 offset:1024
	ds_read_b128 v[170:173], v174 offset:2048
	ds_read_b128 v[174:177], v174 offset:3072
	s_add_u32 s58, s58, 0x80000
	s_addc_u32 s59, s59, 0
	s_mov_b32 m0, s11
	v_lshl_add_u64 v[232:233], s[58:59], 0, v[142:143]
	ds_read_b128 v[178:181], v165 offset:32768
	ds_read_b128 v[182:185], v165 offset:33792
	ds_read_b128 v[186:189], v165 offset:34816
	ds_read_b128 v[190:193], v165 offset:35840
	ds_read_b128 v[204:207], v165 offset:36864
	ds_read_b128 v[218:221], v165 offset:37888
	ds_read_b128 v[222:225], v165 offset:38912
	ds_read_b128 v[226:229], v165 offset:39936
	global_load_lds_dwordx4 v[232:233], off
	v_lshl_add_u64 v[232:233], s[58:59], 0, v[144:145]
	s_mov_b32 m0, s33
	s_nop 0
	global_load_lds_dwordx4 v[232:233], off
	s_waitcnt vmcnt(8)
	s_waitcnt lgkmcnt(0)
	s_barrier
	s_setprio 1
	s_waitcnt lgkmcnt(0)
	v_mfma_f32_16x16x32_bf16 v[126:129], v[130:133], v[178:181], v[126:129]
	v_mfma_f32_16x16x32_bf16 v[122:125], v[138:141], v[178:181], v[122:125]
	v_mfma_f32_16x16x32_bf16 v[110:113], v[130:133], v[186:189], v[110:113]
	v_mfma_f32_16x16x32_bf16 v[106:109], v[138:141], v[186:189], v[106:109]
	v_mfma_f32_16x16x32_bf16 v[94:97], v[130:133], v[204:207], v[94:97]
	v_mfma_f32_16x16x32_bf16 v[90:93], v[138:141], v[204:207], v[90:93]
	v_mfma_f32_16x16x32_bf16 v[78:81], v[130:133], v[222:225], v[78:81]
	v_mfma_f32_16x16x32_bf16 v[74:77], v[138:141], v[222:225], v[74:77]
	v_mfma_f32_16x16x32_bf16 v[126:129], v[134:137], v[182:185], v[126:129]
	v_mfma_f32_16x16x32_bf16 v[122:125], v[152:155], v[182:185], v[122:125]
	v_mfma_f32_16x16x32_bf16 v[110:113], v[134:137], v[190:193], v[110:113]
	v_mfma_f32_16x16x32_bf16 v[106:109], v[152:155], v[190:193], v[106:109]
	v_mfma_f32_16x16x32_bf16 v[94:97], v[134:137], v[218:221], v[94:97]
	v_mfma_f32_16x16x32_bf16 v[90:93], v[152:155], v[218:221], v[90:93]
	v_mfma_f32_16x16x32_bf16 v[78:81], v[134:137], v[226:229], v[78:81]
	v_mfma_f32_16x16x32_bf16 v[74:77], v[152:155], v[226:229], v[74:77]
	s_setprio 0
	s_setprio 1
	v_mfma_f32_16x16x32_bf16 v[118:121], v[156:159], v[178:181], v[118:121]
	v_mfma_f32_16x16x32_bf16 v[114:117], v[170:173], v[178:181], v[114:117]
	v_mfma_f32_16x16x32_bf16 v[102:105], v[156:159], v[186:189], v[102:105]
	v_mfma_f32_16x16x32_bf16 v[98:101], v[170:173], v[186:189], v[98:101]
	v_mfma_f32_16x16x32_bf16 v[86:89], v[156:159], v[204:207], v[86:89]
	v_mfma_f32_16x16x32_bf16 v[82:85], v[170:173], v[204:207], v[82:85]
	v_mfma_f32_16x16x32_bf16 v[70:73], v[156:159], v[222:225], v[70:73]
	v_mfma_f32_16x16x32_bf16 v[66:69], v[170:173], v[222:225], v[66:69]
	v_mfma_f32_16x16x32_bf16 v[118:121], v[166:169], v[182:185], v[118:121]
	v_mfma_f32_16x16x32_bf16 v[114:117], v[174:177], v[182:185], v[114:117]
	v_mfma_f32_16x16x32_bf16 v[102:105], v[166:169], v[190:193], v[102:105]
	v_mfma_f32_16x16x32_bf16 v[98:101], v[174:177], v[190:193], v[98:101]
	v_mfma_f32_16x16x32_bf16 v[86:89], v[166:169], v[218:221], v[86:89]
	v_mfma_f32_16x16x32_bf16 v[82:85], v[174:177], v[218:221], v[82:85]
	v_mfma_f32_16x16x32_bf16 v[70:73], v[166:169], v[226:229], v[70:73]
	v_mfma_f32_16x16x32_bf16 v[66:69], v[174:177], v[226:229], v[66:69]
	s_setprio 0
	s_barrier
; #define PG8_STAGE(bufoff, gbase, voff) do { _Pragma("unroll") for (int _i = 0; _i < 2; ++_i) \
;         __builtin_amdgcn_global_load_lds((const unsigned*)((const char*)(gbase) + (voff)[_i]), (PG8_LAS unsigned*)(lds + (bufoff) + ldsw + _i * 8192), 16, 0, 0); } while (0)
; #define PG8_LDA(dst, b, h) do { _Pragma("unroll") for (int m = 0; m < 4; ++m) _Pragma("unroll") for (int k = 0; k < 2; ++k) dst[m][k] = *(const PG8_LAS bf16x8*)(lds + PG8_SA(b, h) + aoff + m * 2048 + k * 1024); } while (0)
; #define PG8_MMA(ai, bj, At, Bt) do { __builtin_amdgcn_s_setprio(1); _Pragma("unroll") for (int m = 0; m < 4; ++m) _Pragma("unroll") for (int n = 0; n < 2; ++n) _Pragma("unroll") for (int k = 0; k < 2; ++k) \
;         acc[ai][bj][m][n] = __builtin_amdgcn_mfma_f32_16x16x32_bf16(Bt[n][k], At[m][k], acc[ai][bj][m][n], 0, 0, 0); __builtin_amdgcn_s_setprio(0); } while (0)
; #define PG8_WAIT_V(n) asm volatile("s_waitcnt vmcnt(" #n ")" ::: "memory")
; #define PG8_WAIT_L(n) asm volatile("s_waitcnt lgkmcnt(" #n ")" ::: "memory")
; #define PG8_BAR __builtin_amdgcn_s_barrier()
; #define PG8_SCHED __builtin_amdgcn_sched_barrier(0)
; template <class Epi, class Sched, bool ALIGN_EPI = false, bool SP2 = false>
; __device__ __forceinline__ void gemm_phase(PG8_LAS unsigned char* lds, const Gemm g, const Sched& S, const Epi& E) {
;     ...
;         for (int t = 0; t < nt; t += 2) {
;             const bool last = (t == nt - 2);
;             const char* a1 = cA + (size_t)(t + 1) * kstep;
;             const char* a2 = last ? nA : cA + (size_t)(t + 2) * kstep; const char* b2 = last ? nB : cB + (size_t)(t + 2) * kstep;
;             const char* a3 = a2 + kstep; const char* b3 = b2 + kstep;
;             if (last && has_next) S.a_ready(nxt);
;     ...
;             PG8_LDA(At, 1, 1); PG8_STAGE(PG8_SB(1, 0), b3, voffB); PG8_STAGE(PG8_SB(1, 1), b3 + hstep, voffB); PG8_STAGE(PG8_SA(1, 0), a3, voffA);
;             PG8_WAIT_V(8); PG8_WAIT_L(0); PG8_BAR; PG8_MMA(1, 0, At, B0); PG8_MMA(1, 1, At, B1); PG8_BAR; PG8_SCHED;
	s_add_i32 s58, s66, s2
	v_lshl_add_u64 v[160:161], v[160:161], 0, s[56:57]
	s_mov_b32 m0, s58
	ds_read_b128 v[178:181], v165 offset:49152
	ds_read_b128 v[182:185], v165 offset:50176
	ds_read_b128 v[186:189], v165 offset:51200
	ds_read_b128 v[190:193], v165 offset:52224
	ds_read_b128 v[204:207], v165 offset:53248
	ds_read_b128 v[218:221], v165 offset:54272
	ds_read_b128 v[222:225], v165 offset:55296
	ds_read_b128 v[226:229], v165 offset:56320
	global_load_lds_dwordx4 v[160:161], off
	s_add_i32 m0, s58, 0x2000
	s_add_u32 s50, s50, 0x80080
	v_lshl_add_u64 v[160:161], v[200:201], 0, s[56:57]
	s_addc_u32 s51, s51, 0
	s_add_i32 s58, s67, s2
	global_load_lds_dwordx4 v[160:161], off
	v_lshl_add_u64 v[160:161], s[50:51], 0, v[0:1]
	s_mov_b32 m0, s58
	s_nop 0
	global_load_lds_dwordx4 v[160:161], off
	v_lshl_add_u64 v[160:161], s[50:51], 0, v[146:147]
	s_add_i32 m0, s58, 0x2000
	s_nop 0
	global_load_lds_dwordx4 v[160:161], off
	v_lshl_add_u64 v[160:161], v[202:203], 0, s[56:57]
	s_mov_b32 m0, s49
	s_nop 0
	global_load_lds_dwordx4 v[160:161], off
	v_lshl_add_u64 v[160:161], v[230:231], 0, s[56:57]
	s_mov_b32 m0, s54
	s_nop 0
	global_load_lds_dwordx4 v[160:161], off
	s_waitcnt vmcnt(8)
	s_waitcnt lgkmcnt(0)
	s_barrier
	s_setprio 1
	s_waitcnt lgkmcnt(0)
	v_mfma_f32_16x16x32_bf16 v[62:65], v[130:133], v[178:181], v[62:65]
	v_mfma_f32_16x16x32_bf16 v[58:61], v[138:141], v[178:181], v[58:61]
	v_mfma_f32_16x16x32_bf16 v[46:49], v[130:133], v[186:189], v[46:49]
	v_mfma_f32_16x16x32_bf16 v[42:45], v[138:141], v[186:189], v[42:45]
	v_mfma_f32_16x16x32_bf16 v[30:33], v[130:133], v[204:207], v[30:33]
	v_mfma_f32_16x16x32_bf16 v[26:29], v[138:141], v[204:207], v[26:29]
	v_mfma_f32_16x16x32_bf16 v[14:17], v[130:133], v[222:225], v[14:17]
	v_mfma_f32_16x16x32_bf16 v[10:13], v[138:141], v[222:225], v[10:13]
	v_mfma_f32_16x16x32_bf16 v[62:65], v[134:137], v[182:185], v[62:65]
	v_mfma_f32_16x16x32_bf16 v[58:61], v[152:155], v[182:185], v[58:61]
	v_mfma_f32_16x16x32_bf16 v[46:49], v[134:137], v[190:193], v[46:49]
	v_mfma_f32_16x16x32_bf16 v[42:45], v[152:155], v[190:193], v[42:45]
	v_mfma_f32_16x16x32_bf16 v[30:33], v[134:137], v[218:221], v[30:33]
	v_mfma_f32_16x16x32_bf16 v[26:29], v[152:155], v[218:221], v[26:29]
	v_mfma_f32_16x16x32_bf16 v[14:17], v[134:137], v[226:229], v[14:17]
	v_mfma_f32_16x16x32_bf16 v[10:13], v[152:155], v[226:229], v[10:13]
	s_setprio 0
	s_setprio 1
	v_mfma_f32_16x16x32_bf16 v[54:57], v[156:159], v[178:181], v[54:57]
	v_mfma_f32_16x16x32_bf16 v[50:53], v[170:173], v[178:181], v[50:53]
	v_mfma_f32_16x16x32_bf16 v[38:41], v[156:159], v[186:189], v[38:41]
	v_mfma_f32_16x16x32_bf16 v[34:37], v[170:173], v[186:189], v[34:37]
	v_mfma_f32_16x16x32_bf16 v[22:25], v[156:159], v[204:207], v[22:25]
	v_mfma_f32_16x16x32_bf16 v[18:21], v[170:173], v[204:207], v[18:21]
	v_mfma_f32_16x16x32_bf16 v[6:9], v[156:159], v[222:225], v[6:9]
	v_mfma_f32_16x16x32_bf16 v[2:5], v[170:173], v[222:225], v[2:5]
	v_mfma_f32_16x16x32_bf16 v[54:57], v[166:169], v[182:185], v[54:57]
	v_mfma_f32_16x16x32_bf16 v[50:53], v[174:177], v[182:185], v[50:53]
	v_mfma_f32_16x16x32_bf16 v[38:41], v[166:169], v[190:193], v[38:41]
	v_mfma_f32_16x16x32_bf16 v[34:37], v[174:177], v[190:193], v[34:37]
	v_mfma_f32_16x16x32_bf16 v[22:25], v[166:169], v[218:221], v[22:25]
	v_mfma_f32_16x16x32_bf16 v[18:21], v[174:177], v[218:221], v[18:21]
	v_mfma_f32_16x16x32_bf16 v[6:9], v[166:169], v[226:229], v[6:9]
	v_mfma_f32_16x16x32_bf16 v[2:5], v[174:177], v[226:229], v[2:5]
	s_setprio 0
	s_add_i32 s63, s63, 2
	s_add_u32 s24, s24, 0x100
	s_addc_u32 s25, s25, 0
	s_add_u32 s27, s27, 0x100
	s_addc_u32 s62, s62, 0
	s_cmp_gt_u32 s63, 29
	s_cbranch_scc1 .Lgemm_exit_2
	s_add_u32 s50, s24, 0xfff80080
	s_addc_u32 s51, s25, -1
	s_add_i32 s66, 0, 0x10000
	s_cmp_eq_u32 s63, 28
	s_cselect_b32 s59, s15, s51
	s_cselect_b32 s58, s23, s50
	s_cselect_b32 s51, s21, s62
	s_cselect_b32 s50, s26, s27
	s_add_i32 s68, 0, 0x14000
	v_add_u32_e32 v152, s66, v163
	v_add_u32_e32 v160, s68, v163
	s_barrier
	s_branch .Lgemm_body_2
.Lgemm_exit_2:
	s_barrier
	s_and_b64 vcc, exec, s[18:19]
	s_cbranch_vccz .LBB0_492
	s_barrier

; #define PG8_STAGE(bufoff, gbase, voff) do { _Pragma("unroll") for (int _i = 0; _i < 2; ++_i) \
;         __builtin_amdgcn_global_load_lds((const unsigned*)((const char*)(gbase) + (voff)[_i]), (PG8_LAS unsigned*)(lds + (bufoff) + ldsw + _i * 8192), 16, 0, 0); } while (0)
; #define PG8_LDA(dst, b, h) do { _Pragma("unroll") for (int m = 0; m < 4; ++m) _Pragma("unroll") for (int k = 0; k < 2; ++k) dst[m][k] = *(const PG8_LAS bf16x8*)(lds + PG8_SA(b, h) + aoff + m * 2048 + k * 1024); } while (0)
; #define PG8_LDB(dst, b, h) do { _Pragma("unroll") for (int n = 0; n < 2; ++n) _Pragma("unroll") for (int k = 0; k < 2; ++k) dst[n][k] = *(const PG8_LAS bf16x8*)(lds + PG8_SB(b, h) + boff + n * 2048 + k * 1024); } while (0)
; #define PG8_MMA(ai, bj, At, Bt) do { __builtin_amdgcn_s_setprio(1); _Pragma("unroll") for (int m = 0; m < 4; ++m) _Pragma("unroll") for (int n = 0; n < 2; ++n) _Pragma("unroll") for (int k = 0; k < 2; ++k) \
;         acc[ai][bj][m][n] = __builtin_amdgcn_mfma_f32_16x16x32_bf16(Bt[n][k], At[m][k], acc[ai][bj][m][n], 0, 0, 0); __builtin_amdgcn_s_setprio(0); } while (0)
; #define PG8_WAIT_V(n) asm volatile("s_waitcnt vmcnt(" #n ")" ::: "memory")
; #define PG8_WAIT_L(n) asm volatile("s_waitcnt lgkmcnt(" #n ")" ::: "memory")
; #define PG8_BAR __builtin_amdgcn_s_barrier()
; #define PG8_SCHED __builtin_amdgcn_sched_barrier(0)
; template <class Epi, class Sched, bool ALIGN_EPI = false, bool SP2 = false>
; __device__ __forceinline__ void gemm_phase(PG8_LAS unsigned char* lds, const Gemm g, const Sched& S, const Epi& E) {
;     ...
;         for (int t = 0; t < nt; t += 2) {
;             const bool last = (t == nt - 2);
;             const char* a1 = cA + (size_t)(t + 1) * kstep;
;             const char* a2 = last ? nA : cA + (size_t)(t + 2) * kstep; const char* b2 = last ? nB : cB + (size_t)(t + 2) * kstep;
;             const char* a3 = a2 + kstep; const char* b3 = b2 + kstep;
;             if (last && has_next) S.a_ready(nxt);
;             if constexpr (SP2) {
;             PG8_LDB(B0, 0, 0); PG8_LDB(B1, 0, 1); PG8_SCHED; PG8_LDA(At, 0, 0); PG8_STAGE(PG8_SA(1, 1), a1 + hstep, voffA);
;             PG8_WAIT_V(8); PG8_WAIT_L(0); PG8_BAR; PG8_MMA(0, 0, At, B0); PG8_MMA(0, 1, At, B1); PG8_BAR; PG8_SCHED;
;             PG8_LDA(At, 0, 1); PG8_STAGE(PG8_SB(0, 0), b2, voffB); PG8_STAGE(PG8_SB(0, 1), b2 + hstep, voffB); PG8_STAGE(PG8_SA(0, 0), a2, voffA);
.Lgemm_body_3:
	ds_read_b128 v[130:133], v0
	ds_read_b128 v[134:137], v0 offset:1024
	ds_read_b128 v[138:141], v0 offset:2048
	ds_read_b128 v[142:145], v0 offset:3072
	v_add_u32_e32 v0, s73, v192
	ds_read_b128 v[146:149], v0
	ds_read_b128 v[150:153], v0 offset:1024
	ds_read_b128 v[168:171], v0 offset:2048
	ds_read_b128 v[172:175], v0 offset:3072
	v_lshl_add_u64 v[154:155], s[24:25], 0, v[164:165]
	s_add_i32 m0, s77, 0xc000
	ds_read_b128 v[176:179], v193
	ds_read_b128 v[180:183], v193 offset:1024
	ds_read_b128 v[186:189], v193 offset:2048
	ds_read_b128 v[204:207], v193 offset:3072
	ds_read_b128 v[218:221], v193 offset:4096
	ds_read_b128 v[222:225], v193 offset:5120
	ds_read_b128 v[226:229], v193 offset:6144
	ds_read_b128 v[230:233], v193 offset:7168
	global_load_lds_dwordx4 v[154:155], off
	v_lshl_add_u64 v[154:155], s[24:25], 0, v[166:167]
	s_add_i32 m0, s77, 0xe000
	s_nop 0
	global_load_lds_dwordx4 v[154:155], off
	s_waitcnt vmcnt(8)
	s_waitcnt lgkmcnt(0)
	s_barrier
	s_setprio 1
	s_waitcnt lgkmcnt(0)
	v_mfma_f32_16x16x32_bf16 v[126:129], v[130:133], v[176:179], v[126:129]
	v_mfma_f32_16x16x32_bf16 v[122:125], v[138:141], v[176:179], v[122:125]
	v_mfma_f32_16x16x32_bf16 v[110:113], v[130:133], v[186:189], v[110:113]
	v_mfma_f32_16x16x32_bf16 v[106:109], v[138:141], v[186:189], v[106:109]
	v_mfma_f32_16x16x32_bf16 v[94:97], v[130:133], v[218:221], v[94:97]
	v_mfma_f32_16x16x32_bf16 v[90:93], v[138:141], v[218:221], v[90:93]
	v_mfma_f32_16x16x32_bf16 v[78:81], v[130:133], v[226:229], v[78:81]
	v_mfma_f32_16x16x32_bf16 v[74:77], v[138:141], v[226:229], v[74:77]
	v_mfma_f32_16x16x32_bf16 v[126:129], v[134:137], v[180:183], v[126:129]
	v_mfma_f32_16x16x32_bf16 v[122:125], v[142:145], v[180:183], v[122:125]
	v_mfma_f32_16x16x32_bf16 v[110:113], v[134:137], v[204:207], v[110:113]
	v_mfma_f32_16x16x32_bf16 v[106:109], v[142:145], v[204:207], v[106:109]
	v_mfma_f32_16x16x32_bf16 v[94:97], v[134:137], v[222:225], v[94:97]
	v_mfma_f32_16x16x32_bf16 v[90:93], v[142:145], v[222:225], v[90:93]
	v_mfma_f32_16x16x32_bf16 v[78:81], v[134:137], v[230:233], v[78:81]
	v_mfma_f32_16x16x32_bf16 v[74:77], v[142:145], v[230:233], v[74:77]
	s_setprio 0
	s_setprio 1
	v_mfma_f32_16x16x32_bf16 v[114:117], v[146:149], v[176:179], v[114:117]
	v_mfma_f32_16x16x32_bf16 v[118:121], v[168:171], v[176:179], v[118:121]
	v_mfma_f32_16x16x32_bf16 v[98:101], v[146:149], v[186:189], v[98:101]
	v_mfma_f32_16x16x32_bf16 v[102:105], v[168:171], v[186:189], v[102:105]
	v_mfma_f32_16x16x32_bf16 v[82:85], v[146:149], v[218:221], v[82:85]
	v_mfma_f32_16x16x32_bf16 v[86:89], v[168:171], v[218:221], v[86:89]
	v_mfma_f32_16x16x32_bf16 v[66:69], v[146:149], v[226:229], v[66:69]
	v_mfma_f32_16x16x32_bf16 v[70:73], v[168:171], v[226:229], v[70:73]
	v_mfma_f32_16x16x32_bf16 v[114:117], v[150:153], v[180:183], v[114:117]
	v_mfma_f32_16x16x32_bf16 v[118:121], v[172:175], v[180:183], v[118:121]
	v_mfma_f32_16x16x32_bf16 v[98:101], v[150:153], v[204:207], v[98:101]
	v_mfma_f32_16x16x32_bf16 v[102:105], v[172:175], v[204:207], v[102:105]
	v_mfma_f32_16x16x32_bf16 v[82:85], v[150:153], v[222:225], v[82:85]
	v_mfma_f32_16x16x32_bf16 v[86:89], v[172:175], v[222:225], v[86:89]
	v_mfma_f32_16x16x32_bf16 v[66:69], v[150:153], v[230:233], v[66:69]
	v_mfma_f32_16x16x32_bf16 v[70:73], v[172:175], v[230:233], v[70:73]
	s_setprio 0
	s_barrier
	s_add_i32 s74, s74, s76
	v_lshl_add_u64 v[154:155], s[44:45], 0, v[158:159]
	s_mov_b32 m0, s74
	ds_read_b128 v[176:179], v193 offset:16384
	ds_read_b128 v[180:183], v193 offset:17408
	ds_read_b128 v[186:189], v193 offset:18432
	ds_read_b128 v[204:207], v193 offset:19456
	ds_read_b128 v[218:221], v193 offset:20480
	ds_read_b128 v[222:225], v193 offset:21504
	ds_read_b128 v[226:229], v193 offset:22528
	ds_read_b128 v[230:233], v193 offset:23552
	global_load_lds_dwordx4 v[154:155], off
	s_add_i32 m0, s74, 0x2000
	s_add_u32 vcc_lo, s44, 0x80000
	v_lshl_add_u64 v[200:201], s[44:45], 0, v[162:163]
	s_addc_u32 vcc_hi, s45, 0
	s_add_i32 s73, s73, s76
	global_load_lds_dwordx4 v[200:201], off
	v_lshl_add_u64 v[202:203], vcc, 0, v[158:159]
	s_mov_b32 m0, s73
	v_lshl_add_u64 v[234:235], s[48:49], 0, v[160:161]
	global_load_lds_dwordx4 v[202:203], off
	v_lshl_add_u64 v[202:203], vcc, 0, v[162:163]
	s_add_i32 m0, s73, 0x2000
	s_nop 0
	global_load_lds_dwordx4 v[202:203], off
	v_lshl_add_u64 v[202:203], s[48:49], 0, v[156:157]
	s_mov_b32 m0, s77
	s_nop 0
	global_load_lds_dwordx4 v[202:203], off
	s_mov_b32 m0, s78
	s_nop 0
	global_load_lds_dwordx4 v[234:235], off
	s_waitcnt vmcnt(8)
	s_waitcnt lgkmcnt(0)
	s_barrier
; #define PG8_STAGE(bufoff, gbase, voff) do { _Pragma("unroll") for (int _i = 0; _i < 2; ++_i) \
;         __builtin_amdgcn_global_load_lds((const unsigned*)((const char*)(gbase) + (voff)[_i]), (PG8_LAS unsigned*)(lds + (bufoff) + ldsw + _i * 8192), 16, 0, 0); } while (0)
; #define PG8_LDA(dst, b, h) do { _Pragma("unroll") for (int m = 0; m < 4; ++m) _Pragma("unroll") for (int k = 0; k < 2; ++k) dst[m][k] = *(const PG8_LAS bf16x8*)(lds + PG8_SA(b, h) + aoff + m * 2048 + k * 1024); } while (0)
; #define PG8_LDB(dst, b, h) do { _Pragma("unroll") for (int n = 0; n < 2; ++n) _Pragma("unroll") for (int k = 0; k < 2; ++k) dst[n][k] = *(const PG8_LAS bf16x8*)(lds + PG8_SB(b, h) + boff + n * 2048 + k * 1024); } while (0)
; #define PG8_MMA(ai, bj, At, Bt) do { __builtin_amdgcn_s_setprio(1); _Pragma("unroll") for (int m = 0; m < 4; ++m) _Pragma("unroll") for (int n = 0; n < 2; ++n) _Pragma("unroll") for (int k = 0; k < 2; ++k) \
;         acc[ai][bj][m][n] = __builtin_amdgcn_mfma_f32_16x16x32_bf16(Bt[n][k], At[m][k], acc[ai][bj][m][n], 0, 0, 0); __builtin_amdgcn_s_setprio(0); } while (0)
; #define PG8_WAIT_V(n) asm volatile("s_waitcnt vmcnt(" #n ")" ::: "memory")
; #define PG8_WAIT_L(n) asm volatile("s_waitcnt lgkmcnt(" #n ")" ::: "memory")
; #define PG8_BAR __builtin_amdgcn_s_barrier()
; #define PG8_SCHED __builtin_amdgcn_sched_barrier(0)
; template <class Epi, class Sched, bool ALIGN_EPI = false, bool SP2 = false>
; __device__ __forceinline__ void gemm_phase(PG8_LAS unsigned char* lds, const Gemm g, const Sched& S, const Epi& E) {
;     ...
;             PG8_WAIT_V(8); PG8_WAIT_L(0); PG8_BAR; PG8_MMA(1, 0, At, B0); PG8_MMA(1, 1, At, B1); PG8_BAR; PG8_SCHED;
;             PG8_LDB(B0, 1, 0); PG8_LDB(B1, 1, 1); PG8_SCHED; PG8_LDA(At, 1, 0); PG8_STAGE(PG8_SA(0, 1), a2 + hstep, voffA);
;             PG8_WAIT_V(8); PG8_WAIT_L(0); PG8_BAR; PG8_MMA(0, 0, At, B0); PG8_MMA(0, 1, At, B1); PG8_BAR; PG8_SCHED;
	s_setprio 1
	s_waitcnt lgkmcnt(0)
	v_mfma_f32_16x16x32_bf16 v[62:65], v[130:133], v[176:179], v[62:65]
	v_mfma_f32_16x16x32_bf16 v[58:61], v[138:141], v[176:179], v[58:61]
	v_mfma_f32_16x16x32_bf16 v[46:49], v[130:133], v[186:189], v[46:49]
	v_mfma_f32_16x16x32_bf16 v[42:45], v[138:141], v[186:189], v[42:45]
	v_mfma_f32_16x16x32_bf16 v[30:33], v[130:133], v[218:221], v[30:33]
	v_mfma_f32_16x16x32_bf16 v[26:29], v[138:141], v[218:221], v[26:29]
	v_mfma_f32_16x16x32_bf16 v[14:17], v[130:133], v[226:229], v[14:17]
	v_mfma_f32_16x16x32_bf16 v[10:13], v[138:141], v[226:229], v[10:13]
	v_mfma_f32_16x16x32_bf16 v[62:65], v[134:137], v[180:183], v[62:65]
	v_mfma_f32_16x16x32_bf16 v[58:61], v[142:145], v[180:183], v[58:61]
	v_mfma_f32_16x16x32_bf16 v[46:49], v[134:137], v[204:207], v[46:49]
	v_mfma_f32_16x16x32_bf16 v[42:45], v[142:145], v[204:207], v[42:45]
	v_mfma_f32_16x16x32_bf16 v[30:33], v[134:137], v[222:225], v[30:33]
	v_mfma_f32_16x16x32_bf16 v[26:29], v[142:145], v[222:225], v[26:29]
	v_mfma_f32_16x16x32_bf16 v[14:17], v[134:137], v[230:233], v[14:17]
	v_mfma_f32_16x16x32_bf16 v[10:13], v[142:145], v[230:233], v[10:13]
	s_setprio 0
	s_setprio 1
	v_mfma_f32_16x16x32_bf16 v[50:53], v[146:149], v[176:179], v[50:53]
	v_mfma_f32_16x16x32_bf16 v[54:57], v[168:171], v[176:179], v[54:57]
	v_mfma_f32_16x16x32_bf16 v[34:37], v[146:149], v[186:189], v[34:37]
	v_mfma_f32_16x16x32_bf16 v[38:41], v[168:171], v[186:189], v[38:41]
	v_mfma_f32_16x16x32_bf16 v[18:21], v[146:149], v[218:221], v[18:21]
	v_mfma_f32_16x16x32_bf16 v[22:25], v[168:171], v[218:221], v[22:25]
	v_mfma_f32_16x16x32_bf16 v[2:5], v[146:149], v[226:229], v[2:5]
	v_mfma_f32_16x16x32_bf16 v[6:9], v[168:171], v[226:229], v[6:9]
	v_mfma_f32_16x16x32_bf16 v[50:53], v[150:153], v[180:183], v[50:53]
	v_mfma_f32_16x16x32_bf16 v[54:57], v[172:175], v[180:183], v[54:57]
	v_mfma_f32_16x16x32_bf16 v[34:37], v[150:153], v[204:207], v[34:37]
	v_mfma_f32_16x16x32_bf16 v[38:41], v[172:175], v[204:207], v[38:41]
	v_mfma_f32_16x16x32_bf16 v[18:21], v[150:153], v[222:225], v[18:21]
	v_mfma_f32_16x16x32_bf16 v[22:25], v[172:175], v[222:225], v[22:25]
	v_mfma_f32_16x16x32_bf16 v[2:5], v[150:153], v[230:233], v[2:5]
	v_mfma_f32_16x16x32_bf16 v[6:9], v[172:175], v[230:233], v[6:9]
	s_setprio 0
	s_barrier
	s_add_i32 s73, 0, 0x18000
	v_add_u32_e32 v0, s73, v192
	s_add_i32 s74, 0, 0x1c000
	ds_read_b128 v[130:133], v0
	ds_read_b128 v[134:137], v0 offset:1024
	ds_read_b128 v[138:141], v0 offset:2048
	ds_read_b128 v[142:145], v0 offset:3072
	v_add_u32_e32 v0, s74, v192
	ds_read_b128 v[146:149], v0
	ds_read_b128 v[150:153], v0 offset:1024
	ds_read_b128 v[168:171], v0 offset:2048
	ds_read_b128 v[172:175], v0 offset:3072
	s_add_u32 s48, s48, 0x80000
	s_addc_u32 s49, s49, 0
	s_mov_b32 m0, s79
	v_lshl_add_u64 v[236:237], s[48:49], 0, v[156:157]
	ds_read_b128 v[176:179], v193 offset:32768
	ds_read_b128 v[180:183], v193 offset:33792
	ds_read_b128 v[186:189], v193 offset:34816
	ds_read_b128 v[204:207], v193 offset:35840
	ds_read_b128 v[218:221], v193 offset:36864
	ds_read_b128 v[222:225], v193 offset:37888
	ds_read_b128 v[226:229], v193 offset:38912
	ds_read_b128 v[230:233], v193 offset:39936
	global_load_lds_dwordx4 v[236:237], off
	v_lshl_add_u64 v[236:237], s[48:49], 0, v[160:161]
	s_mov_b32 m0, s80
	s_nop 0
	global_load_lds_dwordx4 v[236:237], off
	s_waitcnt vmcnt(8)
	s_waitcnt lgkmcnt(0)
	s_barrier
	s_setprio 1
	s_waitcnt lgkmcnt(0)
	v_mfma_f32_16x16x32_bf16 v[126:129], v[130:133], v[176:179], v[126:129]
	v_mfma_f32_16x16x32_bf16 v[122:125], v[138:141], v[176:179], v[122:125]
	v_mfma_f32_16x16x32_bf16 v[110:113], v[130:133], v[186:189], v[110:113]
	v_mfma_f32_16x16x32_bf16 v[106:109], v[138:141], v[186:189], v[106:109]
	v_mfma_f32_16x16x32_bf16 v[94:97], v[130:133], v[218:221], v[94:97]
	v_mfma_f32_16x16x32_bf16 v[90:93], v[138:141], v[218:221], v[90:93]
	v_mfma_f32_16x16x32_bf16 v[78:81], v[130:133], v[226:229], v[78:81]
	v_mfma_f32_16x16x32_bf16 v[74:77], v[138:141], v[226:229], v[74:77]
	v_mfma_f32_16x16x32_bf16 v[126:129], v[134:137], v[180:183], v[126:129]
	v_mfma_f32_16x16x32_bf16 v[122:125], v[142:145], v[180:183], v[122:125]
	v_mfma_f32_16x16x32_bf16 v[110:113], v[134:137], v[204:207], v[110:113]
	v_mfma_f32_16x16x32_bf16 v[106:109], v[142:145], v[204:207], v[106:109]
	v_mfma_f32_16x16x32_bf16 v[94:97], v[134:137], v[222:225], v[94:97]
	v_mfma_f32_16x16x32_bf16 v[90:93], v[142:145], v[222:225], v[90:93]
	v_mfma_f32_16x16x32_bf16 v[78:81], v[134:137], v[230:233], v[78:81]
	v_mfma_f32_16x16x32_bf16 v[74:77], v[142:145], v[230:233], v[74:77]
	s_setprio 0
	s_setprio 1
	v_mfma_f32_16x16x32_bf16 v[114:117], v[146:149], v[176:179], v[114:117]
	v_mfma_f32_16x16x32_bf16 v[118:121], v[168:171], v[176:179], v[118:121]
	v_mfma_f32_16x16x32_bf16 v[98:101], v[146:149], v[186:189], v[98:101]
	v_mfma_f32_16x16x32_bf16 v[102:105], v[168:171], v[186:189], v[102:105]
	v_mfma_f32_16x16x32_bf16 v[82:85], v[146:149], v[218:221], v[82:85]
	v_mfma_f32_16x16x32_bf16 v[86:89], v[168:171], v[218:221], v[86:89]
	v_mfma_f32_16x16x32_bf16 v[66:69], v[146:149], v[226:229], v[66:69]
	v_mfma_f32_16x16x32_bf16 v[70:73], v[168:171], v[226:229], v[70:73]
	v_mfma_f32_16x16x32_bf16 v[114:117], v[150:153], v[180:183], v[114:117]
	v_mfma_f32_16x16x32_bf16 v[118:121], v[172:175], v[180:183], v[118:121]
	v_mfma_f32_16x16x32_bf16 v[98:101], v[150:153], v[204:207], v[98:101]
	v_mfma_f32_16x16x32_bf16 v[102:105], v[172:175], v[204:207], v[102:105]
	v_mfma_f32_16x16x32_bf16 v[82:85], v[150:153], v[222:225], v[82:85]
	v_mfma_f32_16x16x32_bf16 v[86:89], v[172:175], v[222:225], v[86:89]
	v_mfma_f32_16x16x32_bf16 v[66:69], v[150:153], v[230:233], v[66:69]
	v_mfma_f32_16x16x32_bf16 v[70:73], v[172:175], v[230:233], v[70:73]
	s_setprio 0
	s_barrier
; #define PG8_STAGE(bufoff, gbase, voff) do { _Pragma("unroll") for (int _i = 0; _i < 2; ++_i) \
;         __builtin_amdgcn_global_load_lds((const unsigned*)((const char*)(gbase) + (voff)[_i]), (PG8_LAS unsigned*)(lds + (bufoff) + ldsw + _i * 8192), 16, 0, 0); } while (0)
; #define PG8_LDA(dst, b, h) do { _Pragma("unroll") for (int m = 0; m < 4; ++m) _Pragma("unroll") for (int k = 0; k < 2; ++k) dst[m][k] = *(const PG8_LAS bf16x8*)(lds + PG8_SA(b, h) + aoff + m * 2048 + k * 1024); } while (0)
; #define PG8_MMA(ai, bj, At, Bt) do { __builtin_amdgcn_s_setprio(1); _Pragma("unroll") for (int m = 0; m < 4; ++m) _Pragma("unroll") for (int n = 0; n < 2; ++n) _Pragma("unroll") for (int k = 0; k < 2; ++k) \
;         acc[ai][bj][m][n] = __builtin_amdgcn_mfma_f32_16x16x32_bf16(Bt[n][k], At[m][k], acc[ai][bj][m][n], 0, 0, 0); __builtin_amdgcn_s_setprio(0); } while (0)
; #define PG8_WAIT_V(n) asm volatile("s_waitcnt vmcnt(" #n ")" ::: "memory")
; #define PG8_WAIT_L(n) asm volatile("s_waitcnt lgkmcnt(" #n ")" ::: "memory")
; #define PG8_BAR __builtin_amdgcn_s_barrier()
; #define PG8_SCHED __builtin_amdgcn_sched_barrier(0)
; template <class Epi, class Sched, bool ALIGN_EPI = false, bool SP2 = false>
; __device__ __forceinline__ void gemm_phase(PG8_LAS unsigned char* lds, const Gemm g, const Sched& S, const Epi& E) {
;     ...
;         for (int t = 0; t < nt; t += 2) {
;             const bool last = (t == nt - 2);
;             const char* a1 = cA + (size_t)(t + 1) * kstep;
;             const char* a2 = last ? nA : cA + (size_t)(t + 2) * kstep; const char* b2 = last ? nB : cB + (size_t)(t + 2) * kstep;
;             const char* a3 = a2 + kstep; const char* b3 = b2 + kstep;
;             if (last && has_next) S.a_ready(nxt);
;     ...
;             PG8_LDA(At, 1, 1); PG8_STAGE(PG8_SB(1, 0), b3, voffB); PG8_STAGE(PG8_SB(1, 1), b3 + hstep, voffB); PG8_STAGE(PG8_SA(1, 0), a3, voffA);
;             PG8_WAIT_V(8); PG8_WAIT_L(0); PG8_BAR; PG8_MMA(1, 0, At, B0); PG8_MMA(1, 1, At, B1); PG8_BAR; PG8_SCHED;
	s_add_i32 s48, s73, s76
	v_lshl_add_u64 v[154:155], v[154:155], 0, s[56:57]
	s_mov_b32 m0, s48
	ds_read_b128 v[176:179], v193 offset:49152
	ds_read_b128 v[180:183], v193 offset:50176
	ds_read_b128 v[186:189], v193 offset:51200
	ds_read_b128 v[204:207], v193 offset:52224
	ds_read_b128 v[218:221], v193 offset:53248
	ds_read_b128 v[222:225], v193 offset:54272
	ds_read_b128 v[226:229], v193 offset:55296
	ds_read_b128 v[230:233], v193 offset:56320
	global_load_lds_dwordx4 v[154:155], off
	s_add_i32 m0, s48, 0x2000
	s_add_u32 s44, s44, 0x80080
	v_lshl_add_u64 v[154:155], v[200:201], 0, s[56:57]
	s_addc_u32 s45, s45, 0
	s_add_i32 s48, s74, s76
	global_load_lds_dwordx4 v[154:155], off
	v_lshl_add_u64 v[154:155], s[44:45], 0, v[158:159]
	s_mov_b32 m0, s48
	s_nop 0
	global_load_lds_dwordx4 v[154:155], off
	v_lshl_add_u64 v[154:155], s[44:45], 0, v[162:163]
	s_add_i32 m0, s48, 0x2000
	s_nop 0
	global_load_lds_dwordx4 v[154:155], off
	v_lshl_add_u64 v[154:155], v[202:203], 0, s[56:57]
	s_mov_b32 m0, s88
	s_nop 0
	global_load_lds_dwordx4 v[154:155], off
	v_lshl_add_u64 v[154:155], v[234:235], 0, s[56:57]
	s_mov_b32 m0, s37
	s_nop 0
	global_load_lds_dwordx4 v[154:155], off
	s_waitcnt vmcnt(8)
	s_waitcnt lgkmcnt(0)
	s_barrier
	s_setprio 1
	s_waitcnt lgkmcnt(0)
	v_mfma_f32_16x16x32_bf16 v[62:65], v[130:133], v[176:179], v[62:65]
	v_mfma_f32_16x16x32_bf16 v[58:61], v[138:141], v[176:179], v[58:61]
	v_mfma_f32_16x16x32_bf16 v[46:49], v[130:133], v[186:189], v[46:49]
	v_mfma_f32_16x16x32_bf16 v[42:45], v[138:141], v[186:189], v[42:45]
	v_mfma_f32_16x16x32_bf16 v[30:33], v[130:133], v[218:221], v[30:33]
	v_mfma_f32_16x16x32_bf16 v[26:29], v[138:141], v[218:221], v[26:29]
	v_mfma_f32_16x16x32_bf16 v[14:17], v[130:133], v[226:229], v[14:17]
	v_mfma_f32_16x16x32_bf16 v[10:13], v[138:141], v[226:229], v[10:13]
	v_mfma_f32_16x16x32_bf16 v[62:65], v[134:137], v[180:183], v[62:65]
	v_mfma_f32_16x16x32_bf16 v[58:61], v[142:145], v[180:183], v[58:61]
	v_mfma_f32_16x16x32_bf16 v[46:49], v[134:137], v[204:207], v[46:49]
	v_mfma_f32_16x16x32_bf16 v[42:45], v[142:145], v[204:207], v[42:45]
	v_mfma_f32_16x16x32_bf16 v[30:33], v[134:137], v[222:225], v[30:33]
	v_mfma_f32_16x16x32_bf16 v[26:29], v[142:145], v[222:225], v[26:29]
	v_mfma_f32_16x16x32_bf16 v[14:17], v[134:137], v[230:233], v[14:17]
	v_mfma_f32_16x16x32_bf16 v[10:13], v[142:145], v[230:233], v[10:13]
	s_setprio 0
	s_setprio 1
	v_mfma_f32_16x16x32_bf16 v[50:53], v[146:149], v[176:179], v[50:53]
	v_mfma_f32_16x16x32_bf16 v[54:57], v[168:171], v[176:179], v[54:57]
	v_mfma_f32_16x16x32_bf16 v[34:37], v[146:149], v[186:189], v[34:37]
	v_mfma_f32_16x16x32_bf16 v[38:41], v[168:171], v[186:189], v[38:41]
	v_mfma_f32_16x16x32_bf16 v[18:21], v[146:149], v[218:221], v[18:21]
	v_mfma_f32_16x16x32_bf16 v[22:25], v[168:171], v[218:221], v[22:25]
	v_mfma_f32_16x16x32_bf16 v[2:5], v[146:149], v[226:229], v[2:5]
	v_mfma_f32_16x16x32_bf16 v[6:9], v[168:171], v[226:229], v[6:9]
	v_mfma_f32_16x16x32_bf16 v[50:53], v[150:153], v[180:183], v[50:53]
	v_mfma_f32_16x16x32_bf16 v[54:57], v[172:175], v[180:183], v[54:57]
	v_mfma_f32_16x16x32_bf16 v[34:37], v[150:153], v[204:207], v[34:37]
	v_mfma_f32_16x16x32_bf16 v[38:41], v[172:175], v[204:207], v[38:41]
	v_mfma_f32_16x16x32_bf16 v[18:21], v[150:153], v[222:225], v[18:21]
	v_mfma_f32_16x16x32_bf16 v[22:25], v[172:175], v[222:225], v[22:25]
	v_mfma_f32_16x16x32_bf16 v[2:5], v[150:153], v[230:233], v[2:5]
	v_mfma_f32_16x16x32_bf16 v[6:9], v[172:175], v[230:233], v[6:9]
	s_setprio 0
	s_add_i32 s51, s51, 2
	s_add_u32 s24, s24, 0x100
	s_addc_u32 s25, s25, 0
	s_add_u32 s27, s27, 0x100
	s_addc_u32 s47, s47, 0
	s_cmp_gt_u32 s51, 29
	s_cbranch_scc1 .Lgemm_exit_3
	s_add_u32 s44, s24, 0xfff80080
	s_addc_u32 s45, s25, -1
	s_add_i32 s74, 0, 0x10000
	s_cmp_eq_u32 s51, 28
	s_cselect_b32 s49, s21, s45
	s_cselect_b32 s48, s20, s44
	v_add_u32_e32 v0, s74, v192
	s_cselect_b32 s45, s19, s47
	s_cselect_b32 s44, s26, s27
	s_add_i32 s73, 0, 0x14000
	s_barrier
	s_branch .Lgemm_body_3
.Lgemm_exit_3:
	s_barrier
	s_and_b64 vcc, exec, s[68:69]
	s_cbranch_vccz .LBB0_646
	s_barrier

; #define PG8_STAGE(bufoff, gbase, voff) do { _Pragma("unroll") for (int _i = 0; _i < 2; ++_i) \
;         __builtin_amdgcn_global_load_lds((const unsigned*)((const char*)(gbase) + (voff)[_i]), (PG8_LAS unsigned*)(lds + (bufoff) + ldsw + _i * 8192), 16, 0, 0); } while (0)
; #define PG8_LDA(dst, b, h) do { _Pragma("unroll") for (int m = 0; m < 4; ++m) _Pragma("unroll") for (int k = 0; k < 2; ++k) dst[m][k] = *(const PG8_LAS bf16x8*)(lds + PG8_SA(b, h) + aoff + m * 2048 + k * 1024); } while (0)
; #define PG8_LDB(dst, b, h) do { _Pragma("unroll") for (int n = 0; n < 2; ++n) _Pragma("unroll") for (int k = 0; k < 2; ++k) dst[n][k] = *(const PG8_LAS bf16x8*)(lds + PG8_SB(b, h) + boff + n * 2048 + k * 1024); } while (0)
; #define PG8_MMA(ai, bj, At, Bt) do { __builtin_amdgcn_s_setprio(1); _Pragma("unroll") for (int m = 0; m < 4; ++m) _Pragma("unroll") for (int n = 0; n < 2; ++n) _Pragma("unroll") for (int k = 0; k < 2; ++k) \
;         acc[ai][bj][m][n] = __builtin_amdgcn_mfma_f32_16x16x32_bf16(Bt[n][k], At[m][k], acc[ai][bj][m][n], 0, 0, 0); __builtin_amdgcn_s_setprio(0); } while (0)
; #define PG8_WAIT_V(n) asm volatile("s_waitcnt vmcnt(" #n ")" ::: "memory")
; #define PG8_WAIT_L(n) asm volatile("s_waitcnt lgkmcnt(" #n ")" ::: "memory")
; #define PG8_BAR __builtin_amdgcn_s_barrier()
; #define PG8_SCHED __builtin_amdgcn_sched_barrier(0)
; template <class Epi, class Sched, bool ALIGN_EPI = false, bool SP2 = false>
; __device__ __forceinline__ void gemm_phase(PG8_LAS unsigned char* lds, const Gemm g, const Sched& S, const Epi& E) {
;     ...
;         for (int t = 0; t < nt; t += 2) {
;             const bool last = (t == nt - 2);
;             const char* a1 = cA + (size_t)(t + 1) * kstep;
;             const char* a2 = last ? nA : cA + (size_t)(t + 2) * kstep; const char* b2 = last ? nB : cB + (size_t)(t + 2) * kstep;
;             const char* a3 = a2 + kstep; const char* b3 = b2 + kstep;
;             if (last && has_next) S.a_ready(nxt);
;             if constexpr (SP2) {
;             PG8_LDB(B0, 0, 0); PG8_LDB(B1, 0, 1); PG8_SCHED; PG8_LDA(At, 0, 0); PG8_STAGE(PG8_SA(1, 1), a1 + hstep, voffA);
;             PG8_WAIT_V(8); PG8_WAIT_L(0); PG8_BAR; PG8_MMA(0, 0, At, B0); PG8_MMA(0, 1, At, B1); PG8_BAR; PG8_SCHED;
;             PG8_LDA(At, 0, 1); PG8_STAGE(PG8_SB(0, 0), b2, voffB); PG8_STAGE(PG8_SB(0, 1), b2 + hstep, voffB); PG8_STAGE(PG8_SA(0, 0), a2, voffA);
.Lgemm_body_4:
	ds_read_b128 v[130:133], v152
	ds_read_b128 v[134:137], v152 offset:1024
	ds_read_b128 v[138:141], v152 offset:2048
	ds_read_b128 v[152:155], v152 offset:3072
	ds_read_b128 v[156:159], v160
	ds_read_b128 v[166:169], v160 offset:1024
	ds_read_b128 v[170:173], v160 offset:2048
	ds_read_b128 v[174:177], v160 offset:3072
	v_lshl_add_u64 v[160:161], s[22:23], 0, v[148:149]
	s_add_i32 m0, s2, 0xc000
	ds_read_b128 v[178:181], v165
	ds_read_b128 v[182:185], v165 offset:1024
	ds_read_b128 v[186:189], v165 offset:2048
	ds_read_b128 v[190:193], v165 offset:3072
	ds_read_b128 v[204:207], v165 offset:4096
	ds_read_b128 v[218:221], v165 offset:5120
	ds_read_b128 v[222:225], v165 offset:6144
	ds_read_b128 v[226:229], v165 offset:7168
	global_load_lds_dwordx4 v[160:161], off
	v_lshl_add_u64 v[160:161], s[22:23], 0, v[150:151]
	s_add_i32 m0, s2, 0xe000
	s_nop 0
	global_load_lds_dwordx4 v[160:161], off
	s_waitcnt vmcnt(8)
	s_waitcnt lgkmcnt(0)
	s_barrier
	s_setprio 1
	s_waitcnt lgkmcnt(0)
	v_mfma_f32_16x16x32_bf16 v[126:129], v[130:133], v[178:181], v[126:129]
	v_mfma_f32_16x16x32_bf16 v[122:125], v[138:141], v[178:181], v[122:125]
	v_mfma_f32_16x16x32_bf16 v[110:113], v[130:133], v[186:189], v[110:113]
	v_mfma_f32_16x16x32_bf16 v[106:109], v[138:141], v[186:189], v[106:109]
	v_mfma_f32_16x16x32_bf16 v[94:97], v[130:133], v[204:207], v[94:97]
	v_mfma_f32_16x16x32_bf16 v[90:93], v[138:141], v[204:207], v[90:93]
	v_mfma_f32_16x16x32_bf16 v[78:81], v[130:133], v[222:225], v[78:81]
	v_mfma_f32_16x16x32_bf16 v[74:77], v[138:141], v[222:225], v[74:77]
	v_mfma_f32_16x16x32_bf16 v[126:129], v[134:137], v[182:185], v[126:129]
	v_mfma_f32_16x16x32_bf16 v[122:125], v[152:155], v[182:185], v[122:125]
	v_mfma_f32_16x16x32_bf16 v[110:113], v[134:137], v[190:193], v[110:113]
	v_mfma_f32_16x16x32_bf16 v[106:109], v[152:155], v[190:193], v[106:109]
	v_mfma_f32_16x16x32_bf16 v[94:97], v[134:137], v[218:221], v[94:97]
	v_mfma_f32_16x16x32_bf16 v[90:93], v[152:155], v[218:221], v[90:93]
	v_mfma_f32_16x16x32_bf16 v[78:81], v[134:137], v[226:229], v[78:81]
	v_mfma_f32_16x16x32_bf16 v[74:77], v[152:155], v[226:229], v[74:77]
	s_setprio 0
	s_setprio 1
	v_mfma_f32_16x16x32_bf16 v[118:121], v[156:159], v[178:181], v[118:121]
	v_mfma_f32_16x16x32_bf16 v[114:117], v[170:173], v[178:181], v[114:117]
	v_mfma_f32_16x16x32_bf16 v[102:105], v[156:159], v[186:189], v[102:105]
	v_mfma_f32_16x16x32_bf16 v[98:101], v[170:173], v[186:189], v[98:101]
	v_mfma_f32_16x16x32_bf16 v[86:89], v[156:159], v[204:207], v[86:89]
	v_mfma_f32_16x16x32_bf16 v[82:85], v[170:173], v[204:207], v[82:85]
	v_mfma_f32_16x16x32_bf16 v[70:73], v[156:159], v[222:225], v[70:73]
	v_mfma_f32_16x16x32_bf16 v[66:69], v[170:173], v[222:225], v[66:69]
	v_mfma_f32_16x16x32_bf16 v[118:121], v[166:169], v[182:185], v[118:121]
	v_mfma_f32_16x16x32_bf16 v[114:117], v[174:177], v[182:185], v[114:117]
	v_mfma_f32_16x16x32_bf16 v[102:105], v[166:169], v[190:193], v[102:105]
	v_mfma_f32_16x16x32_bf16 v[98:101], v[174:177], v[190:193], v[98:101]
	v_mfma_f32_16x16x32_bf16 v[86:89], v[166:169], v[218:221], v[86:89]
	v_mfma_f32_16x16x32_bf16 v[82:85], v[174:177], v[218:221], v[82:85]
	v_mfma_f32_16x16x32_bf16 v[70:73], v[166:169], v[226:229], v[70:73]
	v_mfma_f32_16x16x32_bf16 v[66:69], v[174:177], v[226:229], v[66:69]
	s_setprio 0
	s_barrier
	s_add_i32 s22, s59, s1
	v_lshl_add_u64 v[160:161], s[40:41], 0, v[0:1]
	s_mov_b32 m0, s22
	ds_read_b128 v[178:181], v165 offset:16384
	ds_read_b128 v[182:185], v165 offset:17408
	ds_read_b128 v[186:189], v165 offset:18432
	ds_read_b128 v[190:193], v165 offset:19456
	ds_read_b128 v[204:207], v165 offset:20480
	ds_read_b128 v[218:221], v165 offset:21504
	ds_read_b128 v[222:225], v165 offset:22528
	ds_read_b128 v[226:229], v165 offset:23552
	global_load_lds_dwordx4 v[160:161], off
	s_add_i32 m0, s22, 0x2000
	s_add_u32 s22, s40, 0x160000
	v_lshl_add_u64 v[200:201], s[40:41], 0, v[146:147]
	s_addc_u32 s23, s41, 0
	s_add_i32 s59, s62, s1
	global_load_lds_dwordx4 v[200:201], off
	v_lshl_add_u64 v[202:203], s[22:23], 0, v[0:1]
	s_mov_b32 m0, s59
	v_lshl_add_u64 v[230:231], s[44:45], 0, v[144:145]
	global_load_lds_dwordx4 v[202:203], off
	v_lshl_add_u64 v[202:203], s[22:23], 0, v[146:147]
	s_add_i32 m0, s59, 0x2000
	s_nop 0
	global_load_lds_dwordx4 v[202:203], off
	v_lshl_add_u64 v[202:203], s[44:45], 0, v[142:143]
	s_mov_b32 m0, s2
	s_nop 0
	global_load_lds_dwordx4 v[202:203], off
	s_mov_b32 m0, s3
	s_nop 0
	global_load_lds_dwordx4 v[230:231], off
	s_waitcnt vmcnt(8)
	s_waitcnt lgkmcnt(0)
	s_barrier
; #define PG8_STAGE(bufoff, gbase, voff) do { _Pragma("unroll") for (int _i = 0; _i < 2; ++_i) \
;         __builtin_amdgcn_global_load_lds((const unsigned*)((const char*)(gbase) + (voff)[_i]), (PG8_LAS unsigned*)(lds + (bufoff) + ldsw + _i * 8192), 16, 0, 0); } while (0)
; #define PG8_LDA(dst, b, h) do { _Pragma("unroll") for (int m = 0; m < 4; ++m) _Pragma("unroll") for (int k = 0; k < 2; ++k) dst[m][k] = *(const PG8_LAS bf16x8*)(lds + PG8_SA(b, h) + aoff + m * 2048 + k * 1024); } while (0)
; #define PG8_LDB(dst, b, h) do { _Pragma("unroll") for (int n = 0; n < 2; ++n) _Pragma("unroll") for (int k = 0; k < 2; ++k) dst[n][k] = *(const PG8_LAS bf16x8*)(lds + PG8_SB(b, h) + boff + n * 2048 + k * 1024); } while (0)
; #define PG8_MMA(ai, bj, At, Bt) do { __builtin_amdgcn_s_setprio(1); _Pragma("unroll") for (int m = 0; m < 4; ++m) _Pragma("unroll") for (int n = 0; n < 2; ++n) _Pragma("unroll") for (int k = 0; k < 2; ++k) \
;         acc[ai][bj][m][n] = __builtin_amdgcn_mfma_f32_16x16x32_bf16(Bt[n][k], At[m][k], acc[ai][bj][m][n], 0, 0, 0); __builtin_amdgcn_s_setprio(0); } while (0)
; #define PG8_WAIT_V(n) asm volatile("s_waitcnt vmcnt(" #n ")" ::: "memory")
; #define PG8_WAIT_L(n) asm volatile("s_waitcnt lgkmcnt(" #n ")" ::: "memory")
; #define PG8_BAR __builtin_amdgcn_s_barrier()
; #define PG8_SCHED __builtin_amdgcn_sched_barrier(0)
; template <class Epi, class Sched, bool ALIGN_EPI = false, bool SP2 = false>
; __device__ __forceinline__ void gemm_phase(PG8_LAS unsigned char* lds, const Gemm g, const Sched& S, const Epi& E) {
;     ...
;             PG8_WAIT_V(8); PG8_WAIT_L(0); PG8_BAR; PG8_MMA(1, 0, At, B0); PG8_MMA(1, 1, At, B1); PG8_BAR; PG8_SCHED;
;             PG8_LDB(B0, 1, 0); PG8_LDB(B1, 1, 1); PG8_SCHED; PG8_LDA(At, 1, 0); PG8_STAGE(PG8_SA(0, 1), a2 + hstep, voffA);
;             PG8_WAIT_V(8); PG8_WAIT_L(0); PG8_BAR; PG8_MMA(0, 0, At, B0); PG8_MMA(0, 1, At, B1); PG8_BAR; PG8_SCHED;
	s_setprio 1
	s_waitcnt lgkmcnt(0)
	v_mfma_f32_16x16x32_bf16 v[62:65], v[130:133], v[178:181], v[62:65]
	v_mfma_f32_16x16x32_bf16 v[58:61], v[138:141], v[178:181], v[58:61]
	v_mfma_f32_16x16x32_bf16 v[46:49], v[130:133], v[186:189], v[46:49]
	v_mfma_f32_16x16x32_bf16 v[42:45], v[138:141], v[186:189], v[42:45]
	v_mfma_f32_16x16x32_bf16 v[30:33], v[130:133], v[204:207], v[30:33]
	v_mfma_f32_16x16x32_bf16 v[26:29], v[138:141], v[204:207], v[26:29]
	v_mfma_f32_16x16x32_bf16 v[14:17], v[130:133], v[222:225], v[14:17]
	v_mfma_f32_16x16x32_bf16 v[10:13], v[138:141], v[222:225], v[10:13]
	v_mfma_f32_16x16x32_bf16 v[62:65], v[134:137], v[182:185], v[62:65]
	v_mfma_f32_16x16x32_bf16 v[58:61], v[152:155], v[182:185], v[58:61]
	v_mfma_f32_16x16x32_bf16 v[46:49], v[134:137], v[190:193], v[46:49]
	v_mfma_f32_16x16x32_bf16 v[42:45], v[152:155], v[190:193], v[42:45]
	v_mfma_f32_16x16x32_bf16 v[30:33], v[134:137], v[218:221], v[30:33]
	v_mfma_f32_16x16x32_bf16 v[26:29], v[152:155], v[218:221], v[26:29]
	v_mfma_f32_16x16x32_bf16 v[14:17], v[134:137], v[226:229], v[14:17]
	v_mfma_f32_16x16x32_bf16 v[10:13], v[152:155], v[226:229], v[10:13]
	s_setprio 0
	s_setprio 1
	v_mfma_f32_16x16x32_bf16 v[54:57], v[156:159], v[178:181], v[54:57]
	v_mfma_f32_16x16x32_bf16 v[50:53], v[170:173], v[178:181], v[50:53]
	v_mfma_f32_16x16x32_bf16 v[38:41], v[156:159], v[186:189], v[38:41]
	v_mfma_f32_16x16x32_bf16 v[34:37], v[170:173], v[186:189], v[34:37]
	v_mfma_f32_16x16x32_bf16 v[22:25], v[156:159], v[204:207], v[22:25]
	v_mfma_f32_16x16x32_bf16 v[18:21], v[170:173], v[204:207], v[18:21]
	v_mfma_f32_16x16x32_bf16 v[6:9], v[156:159], v[222:225], v[6:9]
	v_mfma_f32_16x16x32_bf16 v[2:5], v[170:173], v[222:225], v[2:5]
	v_mfma_f32_16x16x32_bf16 v[54:57], v[166:169], v[182:185], v[54:57]
	v_mfma_f32_16x16x32_bf16 v[50:53], v[174:177], v[182:185], v[50:53]
	v_mfma_f32_16x16x32_bf16 v[38:41], v[166:169], v[190:193], v[38:41]
	v_mfma_f32_16x16x32_bf16 v[34:37], v[174:177], v[190:193], v[34:37]
	v_mfma_f32_16x16x32_bf16 v[22:25], v[166:169], v[218:221], v[22:25]
	v_mfma_f32_16x16x32_bf16 v[18:21], v[174:177], v[218:221], v[18:21]
	v_mfma_f32_16x16x32_bf16 v[6:9], v[166:169], v[226:229], v[6:9]
	v_mfma_f32_16x16x32_bf16 v[2:5], v[174:177], v[226:229], v[2:5]
	s_setprio 0
	s_barrier
	s_add_i32 s59, 0, 0x18000
	s_add_i32 s62, 0, 0x1c000
	v_add_u32_e32 v152, s59, v163
	v_add_u32_e32 v174, s62, v163
	ds_read_b128 v[130:133], v152
	ds_read_b128 v[134:137], v152 offset:1024
	ds_read_b128 v[138:141], v152 offset:2048
	ds_read_b128 v[152:155], v152 offset:3072
	ds_read_b128 v[156:159], v174
	ds_read_b128 v[166:169], v174 offset:1024
	ds_read_b128 v[170:173], v174 offset:2048
	ds_read_b128 v[174:177], v174 offset:3072
	s_add_u32 s22, s44, 0x160000
	s_addc_u32 s23, s45, 0
	s_mov_b32 m0, s10
	v_lshl_add_u64 v[232:233], s[22:23], 0, v[142:143]
	ds_read_b128 v[178:181], v165 offset:32768
	ds_read_b128 v[182:185], v165 offset:33792
	ds_read_b128 v[186:189], v165 offset:34816
	ds_read_b128 v[190:193], v165 offset:35840
	ds_read_b128 v[204:207], v165 offset:36864
	ds_read_b128 v[218:221], v165 offset:37888
	ds_read_b128 v[222:225], v165 offset:38912
	ds_read_b128 v[226:229], v165 offset:39936
	global_load_lds_dwordx4 v[232:233], off
	v_lshl_add_u64 v[232:233], s[22:23], 0, v[144:145]
	s_mov_b32 m0, s11
	s_nop 0
	global_load_lds_dwordx4 v[232:233], off
	s_waitcnt vmcnt(8)
	s_waitcnt lgkmcnt(0)
	s_barrier
	s_setprio 1
	s_waitcnt lgkmcnt(0)
	v_mfma_f32_16x16x32_bf16 v[126:129], v[130:133], v[178:181], v[126:129]
	v_mfma_f32_16x16x32_bf16 v[122:125], v[138:141], v[178:181], v[122:125]
	v_mfma_f32_16x16x32_bf16 v[110:113], v[130:133], v[186:189], v[110:113]
	v_mfma_f32_16x16x32_bf16 v[106:109], v[138:141], v[186:189], v[106:109]
	v_mfma_f32_16x16x32_bf16 v[94:97], v[130:133], v[204:207], v[94:97]
	v_mfma_f32_16x16x32_bf16 v[90:93], v[138:141], v[204:207], v[90:93]
	v_mfma_f32_16x16x32_bf16 v[78:81], v[130:133], v[222:225], v[78:81]
	v_mfma_f32_16x16x32_bf16 v[74:77], v[138:141], v[222:225], v[74:77]
	v_mfma_f32_16x16x32_bf16 v[126:129], v[134:137], v[182:185], v[126:129]
	v_mfma_f32_16x16x32_bf16 v[122:125], v[152:155], v[182:185], v[122:125]
	v_mfma_f32_16x16x32_bf16 v[110:113], v[134:137], v[190:193], v[110:113]
	v_mfma_f32_16x16x32_bf16 v[106:109], v[152:155], v[190:193], v[106:109]
	v_mfma_f32_16x16x32_bf16 v[94:97], v[134:137], v[218:221], v[94:97]
	v_mfma_f32_16x16x32_bf16 v[90:93], v[152:155], v[218:221], v[90:93]
	v_mfma_f32_16x16x32_bf16 v[78:81], v[134:137], v[226:229], v[78:81]
	v_mfma_f32_16x16x32_bf16 v[74:77], v[152:155], v[226:229], v[74:77]
	s_setprio 0
	s_setprio 1
	v_mfma_f32_16x16x32_bf16 v[118:121], v[156:159], v[178:181], v[118:121]
	v_mfma_f32_16x16x32_bf16 v[114:117], v[170:173], v[178:181], v[114:117]
	v_mfma_f32_16x16x32_bf16 v[102:105], v[156:159], v[186:189], v[102:105]
	v_mfma_f32_16x16x32_bf16 v[98:101], v[170:173], v[186:189], v[98:101]
	v_mfma_f32_16x16x32_bf16 v[86:89], v[156:159], v[204:207], v[86:89]
	v_mfma_f32_16x16x32_bf16 v[82:85], v[170:173], v[204:207], v[82:85]
	v_mfma_f32_16x16x32_bf16 v[70:73], v[156:159], v[222:225], v[70:73]
	v_mfma_f32_16x16x32_bf16 v[66:69], v[170:173], v[222:225], v[66:69]
	v_mfma_f32_16x16x32_bf16 v[118:121], v[166:169], v[182:185], v[118:121]
	v_mfma_f32_16x16x32_bf16 v[114:117], v[174:177], v[182:185], v[114:117]
	v_mfma_f32_16x16x32_bf16 v[102:105], v[166:169], v[190:193], v[102:105]
	v_mfma_f32_16x16x32_bf16 v[98:101], v[174:177], v[190:193], v[98:101]
	v_mfma_f32_16x16x32_bf16 v[86:89], v[166:169], v[218:221], v[86:89]
	v_mfma_f32_16x16x32_bf16 v[82:85], v[174:177], v[218:221], v[82:85]
	v_mfma_f32_16x16x32_bf16 v[70:73], v[166:169], v[226:229], v[70:73]
	v_mfma_f32_16x16x32_bf16 v[66:69], v[174:177], v[226:229], v[66:69]
	s_setprio 0
	s_barrier
; #define PG8_STAGE(bufoff, gbase, voff) do { _Pragma("unroll") for (int _i = 0; _i < 2; ++_i) \
;         __builtin_amdgcn_global_load_lds((const unsigned*)((const char*)(gbase) + (voff)[_i]), (PG8_LAS unsigned*)(lds + (bufoff) + ldsw + _i * 8192), 16, 0, 0); } while (0)
; #define PG8_LDA(dst, b, h) do { _Pragma("unroll") for (int m = 0; m < 4; ++m) _Pragma("unroll") for (int k = 0; k < 2; ++k) dst[m][k] = *(const PG8_LAS bf16x8*)(lds + PG8_SA(b, h) + aoff + m * 2048 + k * 1024); } while (0)
; #define PG8_LDB(dst, b, h) do { _Pragma("unroll") for (int n = 0; n < 2; ++n) _Pragma("unroll") for (int k = 0; k < 2; ++k) dst[n][k] = *(const PG8_LAS bf16x8*)(lds + PG8_SB(b, h) + boff + n * 2048 + k * 1024); } while (0)
; template <class Epi, class Sched, bool ALIGN_EPI = false, bool SP2 = false>
; __device__ __forceinline__ void gemm_phase(PG8_LAS unsigned char* lds, const Gemm g, const Sched& S, const Epi& E) {
;     ...
;         for (int t = 0; t < nt; t += 2) {
;             const bool last = (t == nt - 2);
;             const char* a1 = cA + (size_t)(t + 1) * kstep;
;             const char* a2 = last ? nA : cA + (size_t)(t + 2) * kstep; const char* b2 = last ? nB : cB + (size_t)(t + 2) * kstep;
;             const char* a3 = a2 + kstep; const char* b3 = b2 + kstep;
;             if (last && has_next) S.a_ready(nxt);
;             if constexpr (SP2) {
;             PG8_LDB(B0, 0, 0); PG8_LDB(B1, 0, 1); PG8_SCHED; PG8_LDA(At, 0, 0); PG8_STAGE(PG8_SA(1, 1), a1 + hstep, voffA);
;             PG8_WAIT_V(8); PG8_WAIT_L(0); PG8_BAR; PG8_MMA(0, 0, At, B0); PG8_MMA(0, 1, At, B1); PG8_BAR; PG8_SCHED;
;             PG8_LDA(At, 0, 1); PG8_STAGE(PG8_SB(0, 0), b2, voffB); PG8_STAGE(PG8_SB(0, 1), b2 + hstep, voffB); PG8_STAGE(PG8_SA(0, 0), a2, voffA);
;             PG8_WAIT_V(8); PG8_WAIT_L(0); PG8_BAR; PG8_MMA(1, 0, At, B0); PG8_MMA(1, 1, At, B1); PG8_BAR; PG8_SCHED;
;             PG8_LDB(B0, 1, 0); PG8_LDB(B1, 1, 1); PG8_SCHED; PG8_LDA(At, 1, 0); PG8_STAGE(PG8_SA(0, 1), a2 + hstep, voffA);
;             PG8_WAIT_V(8); PG8_WAIT_L(0); PG8_BAR; PG8_MMA(0, 0, At, B0); PG8_MMA(0, 1, At, B1); PG8_BAR; PG8_SCHED;
;             PG8_LDA(At, 1, 1); PG8_STAGE(PG8_SB(1, 0), b3, voffB); PG8_STAGE(PG8_SB(1, 1), b3 + hstep, voffB); PG8_STAGE(PG8_SA(1, 0), a3, voffA);
;             PG8_WAIT_V(8); PG8_WAIT_L(0); PG8_BAR; PG8_MMA(1, 0, At, B0); PG8_MMA(1, 1, At, B1); PG8_BAR; PG8_SCHED;
	s_add_i32 s22, s59, s1
	v_lshl_add_u64 v[160:161], v[160:161], 0, s[56:57]
	s_mov_b32 m0, s22
	ds_read_b128 v[178:181], v165 offset:49152
	ds_read_b128 v[182:185], v165 offset:50176
	ds_read_b128 v[186:189], v165 offset:51200
	ds_read_b128 v[190:193], v165 offset:52224
	ds_read_b128 v[204:207], v165 offset:53248
	ds_read_b128 v[218:221], v165 offset:54272
	ds_read_b128 v[222:225], v165 offset:55296
	ds_read_b128 v[226:229], v165 offset:56320
	global_load_lds_dwordx4 v[160:161], off
	s_add_i32 m0, s22, 0x2000
	s_add_u32 s22, s40, 0x160080
	v_lshl_add_u64 v[160:161], v[200:201], 0, s[56:57]
	s_addc_u32 s23, s41, 0
	s_add_i32 s40, s62, s1
	global_load_lds_dwordx4 v[160:161], off
	v_lshl_add_u64 v[160:161], s[22:23], 0, v[0:1]
	s_mov_b32 m0, s40
	s_nop 0
	global_load_lds_dwordx4 v[160:161], off
	v_lshl_add_u64 v[160:161], s[22:23], 0, v[146:147]
	s_add_i32 m0, s40, 0x2000
	s_nop 0
	global_load_lds_dwordx4 v[160:161], off
	v_lshl_add_u64 v[160:161], v[202:203], 0, s[56:57]
	s_mov_b32 m0, s37
	s_nop 0
	global_load_lds_dwordx4 v[160:161], off
	v_lshl_add_u64 v[160:161], v[230:231], 0, s[56:57]
	s_mov_b32 m0, s46
	s_nop 0
	global_load_lds_dwordx4 v[160:161], off
	s_waitcnt vmcnt(8)
	s_waitcnt lgkmcnt(0)
	s_barrier
	s_setprio 1
	s_waitcnt lgkmcnt(0)
	v_mfma_f32_16x16x32_bf16 v[62:65], v[130:133], v[178:181], v[62:65]
	v_mfma_f32_16x16x32_bf16 v[58:61], v[138:141], v[178:181], v[58:61]
	v_mfma_f32_16x16x32_bf16 v[46:49], v[130:133], v[186:189], v[46:49]
	v_mfma_f32_16x16x32_bf16 v[42:45], v[138:141], v[186:189], v[42:45]
	v_mfma_f32_16x16x32_bf16 v[30:33], v[130:133], v[204:207], v[30:33]
	v_mfma_f32_16x16x32_bf16 v[26:29], v[138:141], v[204:207], v[26:29]
	v_mfma_f32_16x16x32_bf16 v[14:17], v[130:133], v[222:225], v[14:17]
	v_mfma_f32_16x16x32_bf16 v[10:13], v[138:141], v[222:225], v[10:13]
	v_mfma_f32_16x16x32_bf16 v[62:65], v[134:137], v[182:185], v[62:65]
	v_mfma_f32_16x16x32_bf16 v[58:61], v[152:155], v[182:185], v[58:61]
	v_mfma_f32_16x16x32_bf16 v[46:49], v[134:137], v[190:193], v[46:49]
	v_mfma_f32_16x16x32_bf16 v[42:45], v[152:155], v[190:193], v[42:45]
	v_mfma_f32_16x16x32_bf16 v[30:33], v[134:137], v[218:221], v[30:33]
	v_mfma_f32_16x16x32_bf16 v[26:29], v[152:155], v[218:221], v[26:29]
	v_mfma_f32_16x16x32_bf16 v[14:17], v[134:137], v[226:229], v[14:17]
	v_mfma_f32_16x16x32_bf16 v[10:13], v[152:155], v[226:229], v[10:13]
	s_setprio 0
	s_setprio 1
	v_mfma_f32_16x16x32_bf16 v[54:57], v[156:159], v[178:181], v[54:57]
	v_mfma_f32_16x16x32_bf16 v[50:53], v[170:173], v[178:181], v[50:53]
	v_mfma_f32_16x16x32_bf16 v[38:41], v[156:159], v[186:189], v[38:41]
	v_mfma_f32_16x16x32_bf16 v[34:37], v[170:173], v[186:189], v[34:37]
	v_mfma_f32_16x16x32_bf16 v[22:25], v[156:159], v[204:207], v[22:25]
	v_mfma_f32_16x16x32_bf16 v[18:21], v[170:173], v[204:207], v[18:21]
	v_mfma_f32_16x16x32_bf16 v[6:9], v[156:159], v[222:225], v[6:9]
	v_mfma_f32_16x16x32_bf16 v[2:5], v[170:173], v[222:225], v[2:5]
	v_mfma_f32_16x16x32_bf16 v[54:57], v[166:169], v[182:185], v[54:57]
	v_mfma_f32_16x16x32_bf16 v[50:53], v[174:177], v[182:185], v[50:53]
	v_mfma_f32_16x16x32_bf16 v[38:41], v[166:169], v[190:193], v[38:41]
	v_mfma_f32_16x16x32_bf16 v[34:37], v[174:177], v[190:193], v[34:37]
	v_mfma_f32_16x16x32_bf16 v[22:25], v[166:169], v[218:221], v[22:25]
	v_mfma_f32_16x16x32_bf16 v[18:21], v[174:177], v[218:221], v[18:21]
	v_mfma_f32_16x16x32_bf16 v[6:9], v[166:169], v[226:229], v[6:9]
	v_mfma_f32_16x16x32_bf16 v[2:5], v[174:177], v[226:229], v[2:5]
	s_setprio 0
	s_add_i32 s58, s58, 2
	s_add_u32 s54, s54, 0x100
	s_addc_u32 s55, s55, 0
	s_cmpk_gt_u32 s58, 0x55
	s_mov_b64 s[22:23], s[24:25]
	s_cbranch_scc1 .Lgemm_exit_4
	s_add_u32 s24, s22, 0x100
	s_addc_u32 s25, s23, 0
	s_add_i32 s59, 0, 0x10000
	s_cmpk_eq_i32 s58, 0x54
	s_cselect_b32 s45, s19, s25
	s_cselect_b32 s44, s18, s24
	s_cselect_b32 s41, s21, s55
	s_cselect_b32 s40, s20, s54
	s_add_i32 s62, 0, 0x14000
	v_add_u32_e32 v152, s59, v163
	v_add_u32_e32 v160, s62, v163
	s_barrier
	s_branch .Lgemm_body_4
